# GEMM K-loops: back-edge rotation, loop-back barrier at loop head (strategy 7.11)
# baseline (speedup 1.0000x reference)
.LBB0_137:
	s_ashr_i32 s49, s48, 31
	s_lshl_b64 s[22:23], s[48:49], 20
	s_add_u32 s52, s26, s22
	s_addc_u32 s53, s27, s23
	s_and_b64 s[0:1], s[0:1], exec
	s_cselect_b32 s22, s53, s7
	s_cselect_b32 s23, s52, s6
	s_add_u32 s0, s12, 0x80080
	s_addc_u32 s1, s13, 0
	s_add_u32 s38, s6, 0x100
	v_mov_b64_e32 v[2:3], 0
	s_addc_u32 s39, s7, 0
	s_mov_b32 s49, -2
	v_mov_b64_e32 v[4:5], 0
	v_mov_b64_e32 v[6:7], 0
	v_mov_b64_e32 v[8:9], 0
	v_mov_b64_e32 v[10:11], 0
	v_mov_b64_e32 v[12:13], 0
	v_mov_b64_e32 v[14:15], 0
	v_mov_b64_e32 v[16:17], 0
	v_mov_b64_e32 v[18:19], 0
	v_mov_b64_e32 v[20:21], 0
	v_mov_b64_e32 v[22:23], 0
	v_mov_b64_e32 v[24:25], 0
	v_mov_b64_e32 v[26:27], 0
	v_mov_b64_e32 v[28:29], 0
	v_mov_b64_e32 v[30:31], 0
	v_mov_b64_e32 v[32:33], 0
	v_mov_b64_e32 v[34:35], 0
	v_mov_b64_e32 v[36:37], 0
	v_mov_b64_e32 v[38:39], 0
	v_mov_b64_e32 v[40:41], 0
	v_mov_b64_e32 v[42:43], 0
	v_mov_b64_e32 v[44:45], 0
	v_mov_b64_e32 v[46:47], 0
	v_mov_b64_e32 v[48:49], 0
	v_mov_b64_e32 v[50:51], 0
	v_mov_b64_e32 v[52:53], 0
	v_mov_b64_e32 v[54:55], 0
	v_mov_b64_e32 v[56:57], 0
	v_mov_b64_e32 v[58:59], 0
	v_mov_b64_e32 v[60:61], 0
	v_mov_b64_e32 v[62:63], 0
	v_mov_b64_e32 v[64:65], 0
	v_mov_b64_e32 v[66:67], 0
	v_mov_b64_e32 v[68:69], 0
	v_mov_b64_e32 v[70:71], 0
	v_mov_b64_e32 v[72:73], 0
	v_mov_b64_e32 v[74:75], 0
	v_mov_b64_e32 v[76:77], 0
	v_mov_b64_e32 v[78:79], 0
	v_mov_b64_e32 v[80:81], 0
	v_mov_b64_e32 v[82:83], 0
	v_mov_b64_e32 v[84:85], 0
	v_mov_b64_e32 v[86:87], 0
	v_mov_b64_e32 v[88:89], 0
	v_mov_b64_e32 v[90:91], 0
	v_mov_b64_e32 v[92:93], 0
	v_mov_b64_e32 v[94:95], 0
	v_mov_b64_e32 v[96:97], 0
	v_mov_b64_e32 v[98:99], 0
	v_mov_b64_e32 v[100:101], 0
	v_mov_b64_e32 v[102:103], 0
	v_mov_b64_e32 v[104:105], 0
	v_mov_b64_e32 v[106:107], 0
	v_mov_b64_e32 v[108:109], 0
	v_mov_b64_e32 v[110:111], 0
	v_mov_b64_e32 v[112:113], 0
	v_mov_b64_e32 v[114:115], 0
	v_mov_b64_e32 v[116:117], 0
	v_mov_b64_e32 v[118:119], 0
	v_mov_b64_e32 v[120:121], 0
	v_mov_b64_e32 v[122:123], 0
	v_mov_b64_e32 v[124:125], 0
	v_mov_b64_e32 v[126:127], 0
	v_mov_b64_e32 v[128:129], 0
	v_add_u32_e32 v224, 0x10000, v149
	v_add_u32_e32 v225, 0x14000, v149
	v_add_u32_e32 v226, 0x18000, v149
	v_add_u32_e32 v227, 0x1c000, v149
	s_branch .Lrot138_in

.Lrot138_in:
	s_add_u32 s6, s0, 0xfff80080
	s_addc_u32 s7, s1, -1
	s_add_i32 s76, 0, 0x10000
	ds_read_b128 v[130:133], v224
	ds_read_b128 v[134:137], v224 offset:1024
	ds_read_b128 v[138:141], v224 offset:2048
	ds_read_b128 v[142:145], v224 offset:3072
	s_cmp_eq_u32 s49, 28
	s_cselect_b32 s13, s51, s7
	s_cselect_b32 s12, s50, s6
	s_cselect_b32 s7, s22, s39
	s_cselect_b32 s6, s23, s38
	s_add_i32 m0, s31, 0xc000
	ds_read_b128 v[152:155], v174
	ds_read_b128 v[166:169], v174 offset:1024
	ds_read_b128 v[170:173], v174 offset:2048
	ds_read_b128 v[176:179], v174 offset:3072
	ds_read_b128 v[180:183], v174 offset:4096
	ds_read_b128 v[184:187], v174 offset:5120
	ds_read_b128 v[188:191], v174 offset:6144
	global_load_lds_dwordx4 v162, s[0:1]
	s_add_i32 m0, s31, 0xe000
	ds_read_b128 v[192:195], v174 offset:7168
	global_load_lds_dwordx4 v164, s[0:1]
	s_waitcnt lgkmcnt(8)
	s_barrier
	s_waitcnt lgkmcnt(7)
	v_mfma_f32_16x16x32_bf16 v[126:129], v[130:133], v[152:155], v[126:129]
	v_mfma_f32_16x16x32_bf16 v[122:125], v[138:141], v[152:155], v[122:125]
	s_waitcnt lgkmcnt(5)
	v_mfma_f32_16x16x32_bf16 v[114:117], v[130:133], v[170:173], v[114:117]
	v_mfma_f32_16x16x32_bf16 v[106:109], v[138:141], v[170:173], v[106:109]
	s_waitcnt lgkmcnt(3)
	v_mfma_f32_16x16x32_bf16 v[98:101], v[130:133], v[180:183], v[98:101]
	v_mfma_f32_16x16x32_bf16 v[90:93], v[138:141], v[180:183], v[90:93]
	s_waitcnt lgkmcnt(1)
	v_mfma_f32_16x16x32_bf16 v[82:85], v[130:133], v[188:191], v[82:85]
	v_mfma_f32_16x16x32_bf16 v[74:77], v[138:141], v[188:191], v[74:77]
	v_mfma_f32_16x16x32_bf16 v[126:129], v[134:137], v[166:169], v[126:129]
	v_mfma_f32_16x16x32_bf16 v[122:125], v[142:145], v[166:169], v[122:125]
	v_mfma_f32_16x16x32_bf16 v[114:117], v[134:137], v[176:179], v[114:117]
	v_mfma_f32_16x16x32_bf16 v[106:109], v[142:145], v[176:179], v[106:109]
	v_mfma_f32_16x16x32_bf16 v[98:101], v[134:137], v[184:187], v[98:101]
	v_mfma_f32_16x16x32_bf16 v[90:93], v[142:145], v[184:187], v[90:93]
	s_waitcnt lgkmcnt(0)
	v_mfma_f32_16x16x32_bf16 v[82:85], v[134:137], v[192:195], v[82:85]
	v_mfma_f32_16x16x32_bf16 v[74:77], v[142:145], v[192:195], v[74:77]
	s_barrier
	s_add_i32 s78, 0, 0x14000
	s_add_i32 s76, s76, s30
	s_mov_b32 m0, s76
	ds_read_b128 v[196:199], v225
	ds_read_b128 v[200:203], v225 offset:1024
	ds_read_b128 v[204:207], v225 offset:2048
	global_load_lds_dwordx4 v158, s[6:7]
	s_add_i32 m0, s76, 0x2000
	ds_read_b128 v[216:219], v225 offset:3072
	global_load_lds_dwordx4 v146, s[6:7]
	s_barrier
	s_waitcnt lgkmcnt(3)
	v_mfma_f32_16x16x32_bf16 v[118:121], v[196:199], v[152:155], v[118:121]
	s_waitcnt lgkmcnt(1)
	v_mfma_f32_16x16x32_bf16 v[110:113], v[204:207], v[152:155], v[110:113]
	v_mfma_f32_16x16x32_bf16 v[102:105], v[196:199], v[170:173], v[102:105]
	v_mfma_f32_16x16x32_bf16 v[94:97], v[204:207], v[170:173], v[94:97]
	v_mfma_f32_16x16x32_bf16 v[86:89], v[196:199], v[180:183], v[86:89]
	v_mfma_f32_16x16x32_bf16 v[78:81], v[204:207], v[180:183], v[78:81]
	v_mfma_f32_16x16x32_bf16 v[70:73], v[196:199], v[188:191], v[70:73]
	v_mfma_f32_16x16x32_bf16 v[66:69], v[204:207], v[188:191], v[66:69]
	v_mfma_f32_16x16x32_bf16 v[118:121], v[200:203], v[166:169], v[118:121]
	s_waitcnt lgkmcnt(0)
	v_mfma_f32_16x16x32_bf16 v[110:113], v[216:219], v[166:169], v[110:113]
	v_mfma_f32_16x16x32_bf16 v[102:105], v[200:203], v[176:179], v[102:105]
	v_mfma_f32_16x16x32_bf16 v[94:97], v[216:219], v[176:179], v[94:97]
	v_mfma_f32_16x16x32_bf16 v[86:89], v[200:203], v[184:187], v[86:89]
	v_mfma_f32_16x16x32_bf16 v[78:81], v[216:219], v[184:187], v[78:81]
	v_mfma_f32_16x16x32_bf16 v[70:73], v[200:203], v[192:195], v[70:73]
	v_mfma_f32_16x16x32_bf16 v[66:69], v[216:219], v[192:195], v[66:69]
	s_mov_b32 m0, s31
	s_add_u32 s98, s12, 0x80
	s_addc_u32 s99, s13, 0
	s_barrier
	ds_read_b128 v[152:155], v174 offset:16384
	ds_read_b128 v[166:169], v174 offset:17408
	ds_read_b128 v[170:173], v174 offset:18432
	ds_read_b128 v[176:179], v174 offset:19456
	ds_read_b128 v[180:183], v174 offset:20480
	ds_read_b128 v[184:187], v174 offset:21504
	ds_read_b128 v[188:191], v174 offset:22528
	global_load_lds_dwordx4 v160, s[12:13]
	s_mov_b32 m0, s40
	ds_read_b128 v[192:195], v174 offset:23552
	global_load_lds_dwordx4 v156, s[12:13]
	s_barrier
	s_waitcnt lgkmcnt(7)
	v_mfma_f32_16x16x32_bf16 v[62:65], v[130:133], v[152:155], v[62:65]
	v_mfma_f32_16x16x32_bf16 v[58:61], v[138:141], v[152:155], v[58:61]
	s_waitcnt lgkmcnt(5)
	v_mfma_f32_16x16x32_bf16 v[50:53], v[130:133], v[170:173], v[50:53]
	v_mfma_f32_16x16x32_bf16 v[42:45], v[138:141], v[170:173], v[42:45]
	s_waitcnt lgkmcnt(3)
	v_mfma_f32_16x16x32_bf16 v[34:37], v[130:133], v[180:183], v[34:37]
	v_mfma_f32_16x16x32_bf16 v[26:29], v[138:141], v[180:183], v[26:29]
	s_waitcnt lgkmcnt(1)
	v_mfma_f32_16x16x32_bf16 v[18:21], v[130:133], v[188:191], v[18:21]
	v_mfma_f32_16x16x32_bf16 v[10:13], v[138:141], v[188:191], v[10:13]
	v_mfma_f32_16x16x32_bf16 v[62:65], v[134:137], v[166:169], v[62:65]
	v_mfma_f32_16x16x32_bf16 v[58:61], v[142:145], v[166:169], v[58:61]
	v_mfma_f32_16x16x32_bf16 v[50:53], v[134:137], v[176:179], v[50:53]
	v_mfma_f32_16x16x32_bf16 v[42:45], v[142:145], v[176:179], v[42:45]
	v_mfma_f32_16x16x32_bf16 v[34:37], v[134:137], v[184:187], v[34:37]
	v_mfma_f32_16x16x32_bf16 v[26:29], v[142:145], v[184:187], v[26:29]
	s_waitcnt lgkmcnt(0)
	v_mfma_f32_16x16x32_bf16 v[18:21], v[134:137], v[192:195], v[18:21]
	v_mfma_f32_16x16x32_bf16 v[10:13], v[142:145], v[192:195], v[10:13]
	s_barrier
	s_add_i32 s78, s78, s30
	s_mov_b32 m0, s78
	s_add_u32 s76, s6, 0x80000
	s_addc_u32 s77, s7, 0
	global_load_lds_dwordx4 v158, s[76:77]
	s_add_i32 m0, s78, 0x2000
	s_nop 0
	global_load_lds_dwordx4 v146, s[76:77]
	s_waitcnt vmcnt(6)
	s_barrier
	v_mfma_f32_16x16x32_bf16 v[54:57], v[196:199], v[152:155], v[54:57]
	v_mfma_f32_16x16x32_bf16 v[46:49], v[204:207], v[152:155], v[46:49]
	v_mfma_f32_16x16x32_bf16 v[38:41], v[196:199], v[170:173], v[38:41]
	v_mfma_f32_16x16x32_bf16 v[30:33], v[204:207], v[170:173], v[30:33]
	v_mfma_f32_16x16x32_bf16 v[22:25], v[196:199], v[180:183], v[22:25]
	v_mfma_f32_16x16x32_bf16 v[14:17], v[204:207], v[180:183], v[14:17]
	v_mfma_f32_16x16x32_bf16 v[6:9], v[196:199], v[188:191], v[6:9]
	v_mfma_f32_16x16x32_bf16 v[2:5], v[204:207], v[188:191], v[2:5]
	v_mfma_f32_16x16x32_bf16 v[54:57], v[200:203], v[166:169], v[54:57]
	v_mfma_f32_16x16x32_bf16 v[46:49], v[216:219], v[166:169], v[46:49]
	v_mfma_f32_16x16x32_bf16 v[38:41], v[200:203], v[176:179], v[38:41]
	v_mfma_f32_16x16x32_bf16 v[30:33], v[216:219], v[176:179], v[30:33]
	v_mfma_f32_16x16x32_bf16 v[22:25], v[200:203], v[184:187], v[22:25]
	v_mfma_f32_16x16x32_bf16 v[14:17], v[216:219], v[184:187], v[14:17]
	v_mfma_f32_16x16x32_bf16 v[6:9], v[200:203], v[192:195], v[6:9]
	v_mfma_f32_16x16x32_bf16 v[2:5], v[216:219], v[192:195], v[2:5]
	s_add_i32 s76, 0, 0x18000
	s_barrier
	ds_read_b128 v[130:133], v226
	ds_read_b128 v[134:137], v226 offset:1024
	ds_read_b128 v[138:141], v226 offset:2048
	ds_read_b128 v[142:145], v226 offset:3072
	s_add_u32 s12, s12, 0x80000
	s_addc_u32 s13, s13, 0
	s_mov_b32 m0, s41
	ds_read_b128 v[152:155], v174 offset:32768
	ds_read_b128 v[166:169], v174 offset:33792
	ds_read_b128 v[170:173], v174 offset:34816
	ds_read_b128 v[176:179], v174 offset:35840
	ds_read_b128 v[180:183], v174 offset:36864
	ds_read_b128 v[184:187], v174 offset:37888
	ds_read_b128 v[188:191], v174 offset:38912
	global_load_lds_dwordx4 v160, s[12:13]
	s_mov_b32 m0, s60
	ds_read_b128 v[192:195], v174 offset:39936
	global_load_lds_dwordx4 v156, s[12:13]
	s_waitcnt lgkmcnt(8)
	s_barrier
	s_waitcnt lgkmcnt(7)
	v_mfma_f32_16x16x32_bf16 v[126:129], v[130:133], v[152:155], v[126:129]
	v_mfma_f32_16x16x32_bf16 v[122:125], v[138:141], v[152:155], v[122:125]
	s_waitcnt lgkmcnt(5)
	v_mfma_f32_16x16x32_bf16 v[114:117], v[130:133], v[170:173], v[114:117]
	v_mfma_f32_16x16x32_bf16 v[106:109], v[138:141], v[170:173], v[106:109]
	s_waitcnt lgkmcnt(3)
	v_mfma_f32_16x16x32_bf16 v[98:101], v[130:133], v[180:183], v[98:101]
	v_mfma_f32_16x16x32_bf16 v[90:93], v[138:141], v[180:183], v[90:93]
	s_waitcnt lgkmcnt(1)
	v_mfma_f32_16x16x32_bf16 v[82:85], v[130:133], v[188:191], v[82:85]
	v_mfma_f32_16x16x32_bf16 v[74:77], v[138:141], v[188:191], v[74:77]
	v_mfma_f32_16x16x32_bf16 v[126:129], v[134:137], v[166:169], v[126:129]
	v_mfma_f32_16x16x32_bf16 v[122:125], v[142:145], v[166:169], v[122:125]
	v_mfma_f32_16x16x32_bf16 v[114:117], v[134:137], v[176:179], v[114:117]
	v_mfma_f32_16x16x32_bf16 v[106:109], v[142:145], v[176:179], v[106:109]
	v_mfma_f32_16x16x32_bf16 v[98:101], v[134:137], v[184:187], v[98:101]
	v_mfma_f32_16x16x32_bf16 v[90:93], v[142:145], v[184:187], v[90:93]
	s_waitcnt lgkmcnt(0)
	v_mfma_f32_16x16x32_bf16 v[82:85], v[134:137], v[192:195], v[82:85]
	v_mfma_f32_16x16x32_bf16 v[74:77], v[142:145], v[192:195], v[74:77]
	s_barrier
	s_add_i32 s12, 0, 0x1c000
	s_add_i32 s13, s76, s30
	s_add_u32 s100, s6, 0x80
	s_addc_u32 s101, s7, 0
	s_mov_b32 m0, s13
	ds_read_b128 v[196:199], v227
	ds_read_b128 v[200:203], v227 offset:1024
	ds_read_b128 v[204:207], v227 offset:2048
	global_load_lds_dwordx4 v158, s[100:101]
	s_add_i32 m0, s13, 0x2000
	ds_read_b128 v[216:219], v227 offset:3072
	global_load_lds_dwordx4 v146, s[100:101]
	s_barrier
	s_waitcnt lgkmcnt(3)
	v_mfma_f32_16x16x32_bf16 v[118:121], v[196:199], v[152:155], v[118:121]
	s_waitcnt lgkmcnt(1)
	v_mfma_f32_16x16x32_bf16 v[110:113], v[204:207], v[152:155], v[110:113]
	v_mfma_f32_16x16x32_bf16 v[102:105], v[196:199], v[170:173], v[102:105]
	v_mfma_f32_16x16x32_bf16 v[94:97], v[204:207], v[170:173], v[94:97]
	v_mfma_f32_16x16x32_bf16 v[86:89], v[196:199], v[180:183], v[86:89]
	v_mfma_f32_16x16x32_bf16 v[78:81], v[204:207], v[180:183], v[78:81]
	v_mfma_f32_16x16x32_bf16 v[70:73], v[196:199], v[188:191], v[70:73]
	v_mfma_f32_16x16x32_bf16 v[66:69], v[204:207], v[188:191], v[66:69]
	v_mfma_f32_16x16x32_bf16 v[118:121], v[200:203], v[166:169], v[118:121]
	s_waitcnt lgkmcnt(0)
	v_mfma_f32_16x16x32_bf16 v[110:113], v[216:219], v[166:169], v[110:113]
	v_mfma_f32_16x16x32_bf16 v[102:105], v[200:203], v[176:179], v[102:105]
	v_mfma_f32_16x16x32_bf16 v[94:97], v[216:219], v[176:179], v[94:97]
	v_mfma_f32_16x16x32_bf16 v[86:89], v[200:203], v[184:187], v[86:89]
	v_mfma_f32_16x16x32_bf16 v[78:81], v[216:219], v[184:187], v[78:81]
	v_mfma_f32_16x16x32_bf16 v[70:73], v[200:203], v[192:195], v[70:73]
	v_mfma_f32_16x16x32_bf16 v[66:69], v[216:219], v[192:195], v[66:69]
	s_mov_b32 m0, s64
	s_barrier
	ds_read_b128 v[152:155], v174 offset:49152
	ds_read_b128 v[166:169], v174 offset:50176
	ds_read_b128 v[170:173], v174 offset:51200
	ds_read_b128 v[176:179], v174 offset:52224
	ds_read_b128 v[180:183], v174 offset:53248
	ds_read_b128 v[184:187], v174 offset:54272
	ds_read_b128 v[188:191], v174 offset:55296
	global_load_lds_dwordx4 v160, s[98:99]
	s_mov_b32 m0, s65
	ds_read_b128 v[192:195], v174 offset:56320
	global_load_lds_dwordx4 v156, s[98:99]
	s_barrier
	s_waitcnt lgkmcnt(7)
	v_mfma_f32_16x16x32_bf16 v[62:65], v[130:133], v[152:155], v[62:65]
	v_mfma_f32_16x16x32_bf16 v[58:61], v[138:141], v[152:155], v[58:61]
	s_waitcnt lgkmcnt(5)
	v_mfma_f32_16x16x32_bf16 v[50:53], v[130:133], v[170:173], v[50:53]
	v_mfma_f32_16x16x32_bf16 v[42:45], v[138:141], v[170:173], v[42:45]
	s_waitcnt lgkmcnt(3)
	v_mfma_f32_16x16x32_bf16 v[34:37], v[130:133], v[180:183], v[34:37]
	v_mfma_f32_16x16x32_bf16 v[26:29], v[138:141], v[180:183], v[26:29]
	s_waitcnt lgkmcnt(1)
	v_mfma_f32_16x16x32_bf16 v[18:21], v[130:133], v[188:191], v[18:21]
	v_mfma_f32_16x16x32_bf16 v[10:13], v[138:141], v[188:191], v[10:13]
	v_mfma_f32_16x16x32_bf16 v[62:65], v[134:137], v[166:169], v[62:65]
	v_mfma_f32_16x16x32_bf16 v[58:61], v[142:145], v[166:169], v[58:61]
	v_mfma_f32_16x16x32_bf16 v[50:53], v[134:137], v[176:179], v[50:53]
	v_mfma_f32_16x16x32_bf16 v[42:45], v[142:145], v[176:179], v[42:45]
	v_mfma_f32_16x16x32_bf16 v[34:37], v[134:137], v[184:187], v[34:37]
	v_mfma_f32_16x16x32_bf16 v[26:29], v[142:145], v[184:187], v[26:29]
	s_waitcnt lgkmcnt(0)
	v_mfma_f32_16x16x32_bf16 v[18:21], v[134:137], v[192:195], v[18:21]
	v_mfma_f32_16x16x32_bf16 v[10:13], v[142:145], v[192:195], v[10:13]
	s_barrier
	s_add_i32 s12, s12, s30
	s_mov_b32 m0, s12
	s_add_u32 s6, s6, 0x80080
	s_addc_u32 s7, s7, 0
	global_load_lds_dwordx4 v158, s[6:7]
	s_add_i32 m0, s12, 0x2000
	s_nop 0
	global_load_lds_dwordx4 v146, s[6:7]
	s_waitcnt vmcnt(6)
	s_barrier
	v_mfma_f32_16x16x32_bf16 v[54:57], v[196:199], v[152:155], v[54:57]
	v_mfma_f32_16x16x32_bf16 v[46:49], v[204:207], v[152:155], v[46:49]
	v_mfma_f32_16x16x32_bf16 v[38:41], v[196:199], v[170:173], v[38:41]
	v_mfma_f32_16x16x32_bf16 v[30:33], v[204:207], v[170:173], v[30:33]
	v_mfma_f32_16x16x32_bf16 v[22:25], v[196:199], v[180:183], v[22:25]
	v_mfma_f32_16x16x32_bf16 v[14:17], v[204:207], v[180:183], v[14:17]
	v_mfma_f32_16x16x32_bf16 v[6:9], v[196:199], v[188:191], v[6:9]
	v_mfma_f32_16x16x32_bf16 v[2:5], v[204:207], v[188:191], v[2:5]
	v_mfma_f32_16x16x32_bf16 v[54:57], v[200:203], v[166:169], v[54:57]
	v_mfma_f32_16x16x32_bf16 v[46:49], v[216:219], v[166:169], v[46:49]
	v_mfma_f32_16x16x32_bf16 v[38:41], v[200:203], v[176:179], v[38:41]
	v_mfma_f32_16x16x32_bf16 v[30:33], v[216:219], v[176:179], v[30:33]
	v_mfma_f32_16x16x32_bf16 v[22:25], v[200:203], v[184:187], v[22:25]
	v_mfma_f32_16x16x32_bf16 v[14:17], v[216:219], v[184:187], v[14:17]
	v_mfma_f32_16x16x32_bf16 v[6:9], v[200:203], v[192:195], v[6:9]
	v_mfma_f32_16x16x32_bf16 v[2:5], v[216:219], v[192:195], v[2:5]
	s_add_i32 s49, s49, 2
	s_add_u32 s0, s0, 0x100
	s_addc_u32 s1, s1, 0
	s_add_u32 s38, s38, 0x100
	s_addc_u32 s39, s39, 0
	s_cmp_gt_u32 s49, 29
	s_cbranch_scc0 .LBB0_138
	s_barrier
	v_mov_b32_e32 v0, v148
	s_cmp_gt_i32 s69, 15
	v_and_b32_e32 v176, 15, v0
	v_bfe_u32 v175, v0, 4, 2
	s_mov_b64 s[0:1], -1
	s_cbranch_scc0 .LBB0_157
	s_cmp_gt_u32 s69, 23
	s_cbranch_scc0 .LBB0_154
	s_cmp_gt_u32 s69, 31
	s_cbranch_scc0 .LBB0_151
	s_cmp_gt_u32 s69, 39
	s_cbranch_scc0 .LBB0_148
	v_mul_f32_e32 v0, 0xbfb8aa3b, v126
	v_exp_f32_e32 v131, v0
	s_lshr_b32 s0, s75, 3
	s_mulk_i32 s0, 0x880
	s_lshl_b32 s1, s75, 8
	v_add_f32_e32 v131, 1.0, v131
	v_rcp_f32_e32 v132, v131
	v_mul_f32_e32 v131, 0xbfb8aa3b, v122
	v_mul_f32_e32 v133, 0xbfb8aa3b, v127
	v_mul_f32_e32 v134, 0xbfb8aa3b, v123
	v_mul_f32_e32 v135, 0xbfb8aa3b, v128
	v_mul_f32_e32 v136, 0xbfb8aa3b, v124
	v_mul_f32_e32 v137, 0xbfb8aa3b, v129
	v_mul_f32_e32 v138, 0xbfb8aa3b, v125
	v_mul_f32_e32 v139, 0xbfb8aa3b, v118
	v_mul_f32_e32 v140, 0xbfb8aa3b, v110
	v_mul_f32_e32 v141, 0xbfb8aa3b, v119
	v_mul_f32_e32 v142, 0xbfb8aa3b, v111
	v_mul_f32_e32 v143, 0xbfb8aa3b, v120
	v_mul_f32_e32 v152, 0xbfb8aa3b, v112
	v_mul_f32_e32 v153, 0xbfb8aa3b, v121
	v_mul_f32_e32 v154, 0xbfb8aa3b, v113
	v_mul_f32_e32 v155, 0xbfb8aa3b, v114
	v_mul_f32_e32 v177, 0xbfb8aa3b, v106
	v_mul_f32_e32 v178, 0xbfb8aa3b, v115
	v_mul_f32_e32 v179, 0xbfb8aa3b, v107
	v_mul_f32_e32 v180, 0xbfb8aa3b, v116
	v_mul_f32_e32 v181, 0xbfb8aa3b, v108
	v_mul_f32_e32 v182, 0xbfb8aa3b, v117
	v_mul_f32_e32 v183, 0xbfb8aa3b, v109
	v_mul_f32_e32 v184, 0xbfb8aa3b, v102
	v_mul_f32_e32 v185, 0xbfb8aa3b, v94
	v_mul_f32_e32 v186, 0xbfb8aa3b, v103
	v_mul_f32_e32 v187, 0xbfb8aa3b, v95
	v_mul_f32_e32 v188, 0xbfb8aa3b, v104
	v_mul_f32_e32 v189, 0xbfb8aa3b, v96
	v_mul_f32_e32 v190, 0xbfb8aa3b, v105
	v_mul_f32_e32 v191, 0xbfb8aa3b, v97
	v_mul_f32_e32 v192, 0xbfb8aa3b, v98
	v_mul_f32_e32 v193, 0xbfb8aa3b, v90
	v_mul_f32_e32 v194, 0xbfb8aa3b, v99
	v_mul_f32_e32 v195, 0xbfb8aa3b, v91
	v_mul_f32_e32 v196, 0xbfb8aa3b, v100
	v_mul_f32_e32 v197, 0xbfb8aa3b, v92
	v_mul_f32_e32 v198, 0xbfb8aa3b, v101
	v_mul_f32_e32 v199, 0xbfb8aa3b, v93
	v_mul_f32_e32 v200, 0xbfb8aa3b, v86
	v_mul_f32_e32 v201, 0xbfb8aa3b, v78
	v_mul_f32_e32 v202, 0xbfb8aa3b, v87
	v_mul_f32_e32 v203, 0xbfb8aa3b, v79
	v_mul_f32_e32 v204, 0xbfb8aa3b, v88
	v_mul_f32_e32 v205, 0xbfb8aa3b, v80
	v_mul_f32_e32 v206, 0xbfb8aa3b, v89
	v_mul_f32_e32 v207, 0xbfb8aa3b, v81
	v_mul_f32_e32 v208, 0xbfb8aa3b, v82
	v_mul_f32_e32 v209, 0xbfb8aa3b, v74
	v_mul_f32_e32 v215, 0xbfb8aa3b, v83
	v_mul_f32_e32 v216, 0xbfb8aa3b, v75
	v_mul_f32_e32 v217, 0xbfb8aa3b, v84
	v_mul_f32_e32 v218, 0xbfb8aa3b, v76
	v_mul_f32_e32 v219, 0xbfb8aa3b, v85
	v_mul_f32_e32 v220, 0xbfb8aa3b, v77
	v_mul_f32_e32 v221, 0xbfb8aa3b, v70
	v_mul_f32_e32 v222, 0xbfb8aa3b, v66
	v_mul_f32_e32 v223, 0xbfb8aa3b, v71
	v_mul_f32_e32 v224, 0xbfb8aa3b, v67
	v_mul_f32_e32 v225, 0xbfb8aa3b, v72
	v_mul_f32_e32 v226, 0xbfb8aa3b, v68
	v_mul_f32_e32 v227, 0xbfb8aa3b, v73
	v_mul_f32_e32 v228, 0xbfb8aa3b, v69
	v_mul_f32_e32 v229, 0xbfb8aa3b, v62
	v_mul_f32_e32 v230, 0xbfb8aa3b, v58
	v_mul_f32_e32 v231, 0xbfb8aa3b, v63
	v_mul_f32_e32 v232, 0xbfb8aa3b, v59
	v_mul_f32_e32 v233, 0xbfb8aa3b, v64
	v_mul_f32_e32 v234, 0xbfb8aa3b, v60
	v_mul_f32_e32 v235, 0xbfb8aa3b, v65
	v_mul_f32_e32 v236, 0xbfb8aa3b, v61
	v_mul_f32_e32 v237, 0xbfb8aa3b, v54
	v_mul_f32_e32 v238, 0xbfb8aa3b, v46
	v_mul_f32_e32 v239, 0xbfb8aa3b, v55
	s_and_b32 s1, s1, 0x700
	s_add_i32 s0, s0, s66
	v_exp_f32_e32 v173, v131
	v_exp_f32_e32 v133, v133
	v_exp_f32_e32 v172, v134
	v_exp_f32_e32 v171, v135
	v_exp_f32_e32 v170, v136
	v_exp_f32_e32 v169, v137
	v_exp_f32_e32 v131, v138
	v_exp_f32_e32 v168, v139
	v_exp_f32_e32 v167, v140
	v_exp_f32_e32 v166, v141
	v_exp_f32_e32 v145, v142
	v_exp_f32_e32 v144, v143
	v_exp_f32_e32 v143, v152
	v_exp_f32_e32 v142, v153
	v_exp_f32_e32 v141, v154
	v_exp_f32_e32 v140, v155
	v_exp_f32_e32 v139, v177
	v_exp_f32_e32 v138, v178
	v_exp_f32_e32 v213, v179
	v_exp_f32_e32 v155, v180
	v_exp_f32_e32 v154, v181
	v_exp_f32_e32 v153, v182
	v_exp_f32_e32 v152, v183
	v_exp_f32_e32 v212, v184
	v_exp_f32_e32 v211, v185
	v_exp_f32_e32 v252, v186
	v_exp_f32_e32 v251, v187
	v_exp_f32_e32 v250, v188
	v_exp_f32_e32 v249, v189
	v_exp_f32_e32 v248, v190
	v_exp_f32_e32 v247, v191
	v_exp_f32_e32 v246, v192
	v_exp_f32_e32 v245, v193
	v_exp_f32_e32 v244, v194
	v_exp_f32_e32 v243, v195
	v_exp_f32_e32 v242, v196
	v_exp_f32_e32 v241, v197
	v_exp_f32_e32 v184, v198
	v_exp_f32_e32 v177, v199
	v_exp_f32_e32 v198, v200
	v_exp_f32_e32 v199, v201
	v_exp_f32_e32 v197, v202
	v_exp_f32_e32 v196, v203
	v_exp_f32_e32 v195, v204
	v_exp_f32_e32 v194, v205
	v_exp_f32_e32 v193, v206
	v_exp_f32_e32 v192, v207
	v_exp_f32_e32 v191, v208
	v_exp_f32_e32 v190, v209
	v_exp_f32_e32 v189, v215
	v_exp_f32_e32 v188, v216
	v_exp_f32_e32 v187, v217
	v_exp_f32_e32 v186, v218
	v_exp_f32_e32 v185, v219
	v_exp_f32_e32 v201, v220
	v_exp_f32_e32 v200, v221
	v_exp_f32_e32 v221, v222
	v_exp_f32_e32 v220, v223
	v_exp_f32_e32 v219, v224
	v_exp_f32_e32 v218, v225
	v_exp_f32_e32 v217, v226
	v_exp_f32_e32 v216, v227
	v_exp_f32_e32 v215, v228
	v_exp_f32_e32 v209, v229
	v_exp_f32_e32 v208, v230
	v_exp_f32_e32 v207, v231
	v_exp_f32_e32 v206, v232
	v_exp_f32_e32 v205, v233
	v_exp_f32_e32 v204, v234
	v_exp_f32_e32 v203, v235
	v_exp_f32_e32 v202, v236
	v_exp_f32_e32 v223, v237
	v_exp_f32_e32 v222, v238
	v_exp_f32_e32 v238, v239
	s_add_i32 s0, s0, s1
	s_lshl_b32 s1, s69, 8
	v_lshl_or_b32 v130, v175, 3, s1
	s_cmp_gt_u32 s69, 47
	v_or_b32_e32 v240, s0, v176
	v_or_b32_e32 v130, s61, v130
	s_mov_b64 s[0:1], -1
	v_mul_f32_e32 v237, 0xbfb8aa3b, v47
	v_mul_f32_e32 v236, 0xbfb8aa3b, v56
	v_mul_f32_e32 v235, 0xbfb8aa3b, v48
	v_mul_f32_e32 v234, 0xbfb8aa3b, v57
	v_mul_f32_e32 v233, 0xbfb8aa3b, v49
	v_mul_f32_e32 v232, 0xbfb8aa3b, v50
	v_mul_f32_e32 v231, 0xbfb8aa3b, v42
	v_mul_f32_e32 v230, 0xbfb8aa3b, v51
	v_mul_f32_e32 v229, 0xbfb8aa3b, v43
	v_mul_f32_e32 v228, 0xbfb8aa3b, v18
	s_cbranch_scc0 .LBB0_145
	v_add_f32_e32 v178, 1.0, v171
	v_rcp_f32_e32 v179, v178
	v_add_f32_e32 v178, 1.0, v170
	v_add_f32_e32 v134, 1.0, v173
	v_add_f32_e32 v135, 1.0, v133
	v_add_f32_e32 v137, 1.0, v172
	v_rcp_f32_e32 v181, v178
	v_add_f32_e32 v178, 1.0, v169
	v_rcp_f32_e32 v134, v134
	v_rcp_f32_e32 v135, v135
	v_rcp_f32_e32 v137, v137
	v_rcp_f32_e32 v180, v178
	v_add_f32_e32 v178, 1.0, v131
	v_rcp_f32_e32 v182, v178
	v_mov_b32_e32 v0, v240
	v_mov_b32_e32 v136, v130
	v_cvt_pk_bf16_f32 v178, v132, v135
	v_cvt_pk_bf16_f32 v179, v179, v180
	v_cvt_pk_bf16_f32 v180, v134, v137
	v_mov_b64_e32 v[134:135], s[8:9]
	v_ashrrev_i32_e32 v137, 31, v136
	v_cvt_pk_bf16_f32 v181, v181, v182
	v_mad_i64_i32 v[182:183], s[0:1], v0, s47, v[134:135]
	v_lshlrev_b64 v[136:137], 1, v[136:137]
	v_lshl_add_u64 v[182:183], v[182:183], 0, v[136:137]
	global_store_dwordx4 v[182:183], v[178:181], off
	s_nop 1
	v_add_f32_e32 v179, 1.0, v167
	v_add_f32_e32 v178, 1.0, v168
	v_rcp_f32_e32 v180, v179
	v_add_f32_e32 v179, 1.0, v166
	v_add_f32_e32 v181, 1.0, v145
	v_add_f32_e32 v239, 1.0, v144
	v_add_f32_e32 v224, 1.0, v143
	v_add_f32_e32 v225, 1.0, v142
	v_add_f32_e32 v226, 1.0, v141
	v_rcp_f32_e32 v178, v178
	v_rcp_f32_e32 v179, v179
	v_rcp_f32_e32 v181, v181
	v_rcp_f32_e32 v239, v239
	v_rcp_f32_e32 v224, v224
	v_rcp_f32_e32 v225, v225
	v_rcp_f32_e32 v226, v226
	v_cvt_pk_bf16_f32 v178, v178, v179
	v_cvt_pk_bf16_f32 v180, v180, v181
	v_cvt_pk_bf16_f32 v179, v239, v225
	v_cvt_pk_bf16_f32 v181, v224, v226
	global_store_dwordx4 v[182:183], v[178:181], off offset:256
	s_nop 1
	v_add_f32_e32 v179, 1.0, v139
	v_add_f32_e32 v178, 1.0, v140
	v_rcp_f32_e32 v180, v179
	v_add_f32_e32 v179, 1.0, v138
	v_add_f32_e32 v183, 1.0, v155
	v_add_f32_e32 v225, 1.0, v153
	v_rcp_f32_e32 v178, v178
	v_rcp_f32_e32 v179, v179
	v_add_f32_e32 v181, 1.0, v213
	v_rcp_f32_e32 v183, v183
	v_add_f32_e32 v224, 1.0, v154
	v_rcp_f32_e32 v225, v225
	v_add_f32_e32 v226, 1.0, v152
	v_rcp_f32_e32 v181, v181
	v_rcp_f32_e32 v224, v224
	v_rcp_f32_e32 v226, v226
	v_add_u32_e32 v182, 16, v0
	v_cvt_pk_bf16_f32 v178, v178, v179
	v_cvt_pk_bf16_f32 v179, v183, v225
	v_mad_i64_i32 v[182:183], s[0:1], v182, s47, v[134:135]
	v_cvt_pk_bf16_f32 v180, v180, v181
	v_cvt_pk_bf16_f32 v181, v224, v226
	v_lshl_add_u64 v[182:183], v[182:183], 0, v[136:137]
	global_store_dwordx4 v[182:183], v[178:181], off
	s_nop 1
	v_add_f32_e32 v179, 1.0, v211
	v_add_f32_e32 v178, 1.0, v212
	v_rcp_f32_e32 v180, v179
	v_add_f32_e32 v179, 1.0, v252
	v_add_f32_e32 v181, 1.0, v251
	v_add_f32_e32 v224, 1.0, v250
	v_add_f32_e32 v225, 1.0, v249
	v_add_f32_e32 v226, 1.0, v248
	v_add_f32_e32 v239, 1.0, v247
	v_rcp_f32_e32 v178, v178
	v_rcp_f32_e32 v179, v179
	v_rcp_f32_e32 v181, v181
	v_rcp_f32_e32 v224, v224
	v_rcp_f32_e32 v225, v225
	v_rcp_f32_e32 v226, v226
	v_rcp_f32_e32 v239, v239
	v_cvt_pk_bf16_f32 v178, v178, v179
	v_cvt_pk_bf16_f32 v180, v180, v181
	v_cvt_pk_bf16_f32 v179, v224, v226
	v_cvt_pk_bf16_f32 v181, v225, v239
	global_store_dwordx4 v[182:183], v[178:181], off offset:256
	s_nop 1
	v_add_f32_e32 v179, 1.0, v245
	v_add_f32_e32 v178, 1.0, v246
	v_rcp_f32_e32 v180, v179
	v_add_f32_e32 v179, 1.0, v244
	v_add_f32_e32 v183, 1.0, v242
	v_add_f32_e32 v225, 1.0, v184
	v_rcp_f32_e32 v178, v178
	v_rcp_f32_e32 v179, v179
	v_add_f32_e32 v181, 1.0, v243
	v_rcp_f32_e32 v183, v183
	v_add_f32_e32 v224, 1.0, v241
	v_rcp_f32_e32 v225, v225
	v_add_f32_e32 v226, 1.0, v177
	v_rcp_f32_e32 v181, v181
	v_rcp_f32_e32 v224, v224
	v_rcp_f32_e32 v226, v226
	v_add_u32_e32 v182, 32, v0
	v_cvt_pk_bf16_f32 v178, v178, v179
	v_cvt_pk_bf16_f32 v179, v183, v225
	v_mad_i64_i32 v[182:183], s[0:1], v182, s47, v[134:135]
	v_cvt_pk_bf16_f32 v180, v180, v181
	v_cvt_pk_bf16_f32 v181, v224, v226
	v_lshl_add_u64 v[182:183], v[182:183], 0, v[136:137]
	global_store_dwordx4 v[182:183], v[178:181], off
	s_nop 1
	v_add_f32_e32 v179, 1.0, v199
	v_add_f32_e32 v178, 1.0, v198
	v_rcp_f32_e32 v180, v179
	v_add_f32_e32 v179, 1.0, v197
	v_add_f32_e32 v181, 1.0, v196
	v_add_f32_e32 v224, 1.0, v195
	v_add_f32_e32 v225, 1.0, v194
	v_add_f32_e32 v226, 1.0, v193
	v_add_f32_e32 v239, 1.0, v192
	v_rcp_f32_e32 v178, v178
	v_rcp_f32_e32 v179, v179
	v_rcp_f32_e32 v181, v181
	v_rcp_f32_e32 v224, v224
	v_rcp_f32_e32 v225, v225
	v_rcp_f32_e32 v226, v226
	v_rcp_f32_e32 v239, v239
	v_cvt_pk_bf16_f32 v178, v178, v179
	v_cvt_pk_bf16_f32 v180, v180, v181
	v_cvt_pk_bf16_f32 v179, v224, v226
	v_cvt_pk_bf16_f32 v181, v225, v239
	global_store_dwordx4 v[182:183], v[178:181], off offset:256
	s_nop 1
	v_add_f32_e32 v179, 1.0, v190
	v_add_f32_e32 v178, 1.0, v191
	v_rcp_f32_e32 v180, v179
	v_add_f32_e32 v179, 1.0, v189
	v_add_f32_e32 v183, 1.0, v187
	v_add_f32_e32 v225, 1.0, v185
	v_rcp_f32_e32 v178, v178
	v_rcp_f32_e32 v179, v179
	v_add_f32_e32 v181, 1.0, v188
	v_rcp_f32_e32 v183, v183
	v_add_f32_e32 v224, 1.0, v186
	v_rcp_f32_e32 v225, v225
	v_add_f32_e32 v226, 1.0, v201
	v_rcp_f32_e32 v181, v181
	v_rcp_f32_e32 v224, v224
	v_rcp_f32_e32 v226, v226
	v_add_u32_e32 v182, 48, v0
	v_cvt_pk_bf16_f32 v178, v178, v179
	v_cvt_pk_bf16_f32 v179, v183, v225
	v_mad_i64_i32 v[182:183], s[0:1], v182, s47, v[134:135]
	v_cvt_pk_bf16_f32 v180, v180, v181
	v_cvt_pk_bf16_f32 v181, v224, v226
	v_lshl_add_u64 v[182:183], v[182:183], 0, v[136:137]
	global_store_dwordx4 v[182:183], v[178:181], off
	s_nop 1
	v_add_f32_e32 v179, 1.0, v221
	v_add_f32_e32 v178, 1.0, v200
	v_rcp_f32_e32 v180, v179
	v_add_f32_e32 v179, 1.0, v220
	v_add_f32_e32 v181, 1.0, v219
	v_add_f32_e32 v224, 1.0, v218
	v_add_f32_e32 v225, 1.0, v217
	v_add_f32_e32 v226, 1.0, v216
	v_add_f32_e32 v239, 1.0, v215
	v_rcp_f32_e32 v178, v178
	v_rcp_f32_e32 v179, v179
	v_rcp_f32_e32 v181, v181
	v_rcp_f32_e32 v224, v224
	v_rcp_f32_e32 v225, v225
	v_rcp_f32_e32 v226, v226
	v_rcp_f32_e32 v239, v239
	v_cvt_pk_bf16_f32 v178, v178, v179
	v_cvt_pk_bf16_f32 v180, v180, v181
	v_cvt_pk_bf16_f32 v179, v224, v226
	v_cvt_pk_bf16_f32 v181, v225, v239
	global_store_dwordx4 v[182:183], v[178:181], off offset:256
	s_nop 1
	v_add_f32_e32 v179, 1.0, v208
	v_add_f32_e32 v178, 1.0, v209
	v_rcp_f32_e32 v180, v179
	v_add_f32_e32 v179, 1.0, v207
	v_add_f32_e32 v183, 1.0, v205
	v_add_f32_e32 v225, 1.0, v203
	v_rcp_f32_e32 v178, v178
	v_rcp_f32_e32 v179, v179
	v_add_f32_e32 v181, 1.0, v206
	v_rcp_f32_e32 v183, v183
	v_add_f32_e32 v224, 1.0, v204
	v_rcp_f32_e32 v225, v225
	v_add_f32_e32 v226, 1.0, v202
	v_rcp_f32_e32 v181, v181
	v_rcp_f32_e32 v224, v224
	v_rcp_f32_e32 v226, v226
	v_add_u32_e32 v182, 0x80, v0
	v_cvt_pk_bf16_f32 v178, v178, v179
	v_cvt_pk_bf16_f32 v179, v183, v225
	v_mad_i64_i32 v[182:183], s[0:1], v182, s47, v[134:135]
	v_cvt_pk_bf16_f32 v180, v180, v181
	v_cvt_pk_bf16_f32 v181, v224, v226
	v_lshl_add_u64 v[182:183], v[182:183], 0, v[136:137]
	global_store_dwordx4 v[182:183], v[178:181], off
	s_nop 1
	v_add_f32_e32 v179, 1.0, v222
	v_rcp_f32_e32 v180, v179
	v_exp_f32_e32 v179, v237
	v_exp_f32_e32 v224, v236
	v_exp_f32_e32 v226, v234
	v_exp_f32_e32 v239, v233
	v_add_f32_e32 v179, 1.0, v179
	v_rcp_f32_e32 v225, v179
	v_exp_f32_e32 v179, v235
	v_add_f32_e32 v178, 1.0, v223
	v_add_f32_e32 v181, 1.0, v238
	v_add_f32_e32 v224, 1.0, v224
	v_add_f32_e32 v179, 1.0, v179
	v_rcp_f32_e32 v227, v179
	v_add_f32_e32 v179, 1.0, v226
	v_add_f32_e32 v226, 1.0, v239
	v_rcp_f32_e32 v178, v178
	v_rcp_f32_e32 v181, v181
	v_rcp_f32_e32 v224, v224
	v_rcp_f32_e32 v179, v179
	v_rcp_f32_e32 v226, v226
	v_cvt_pk_bf16_f32 v178, v178, v181
	v_cvt_pk_bf16_f32 v180, v180, v225
	v_cvt_pk_bf16_f32 v179, v224, v179
	v_cvt_pk_bf16_f32 v181, v227, v226
	global_store_dwordx4 v[182:183], v[178:181], off offset:256
	s_nop 1
	v_exp_f32_e32 v179, v231
	v_mul_f32_e32 v183, 0xbfb8aa3b, v52
	v_mul_f32_e32 v225, 0xbfb8aa3b, v53
	v_exp_f32_e32 v183, v183
	v_add_f32_e32 v179, 1.0, v179
	v_rcp_f32_e32 v181, v179
	v_exp_f32_e32 v179, v229
	v_exp_f32_e32 v225, v225
	v_mul_f32_e32 v226, 0xbfb8aa3b, v45
	v_exp_f32_e32 v178, v232
	v_add_f32_e32 v179, 1.0, v179
	v_rcp_f32_e32 v224, v179
	v_mul_f32_e32 v179, 0xbfb8aa3b, v44
	v_exp_f32_e32 v179, v179
	v_exp_f32_e32 v180, v230
	v_exp_f32_e32 v226, v226
	v_add_f32_e32 v183, 1.0, v183
	v_add_f32_e32 v179, 1.0, v179
	v_rcp_f32_e32 v227, v179
	v_add_f32_e32 v179, 1.0, v225
	v_add_f32_e32 v178, 1.0, v178
	v_add_f32_e32 v180, 1.0, v180
	v_rcp_f32_e32 v183, v183
	v_rcp_f32_e32 v179, v179
	v_add_f32_e32 v225, 1.0, v226
	v_rcp_f32_e32 v178, v178
	v_rcp_f32_e32 v180, v180
	v_rcp_f32_e32 v225, v225
	v_add_u32_e32 v182, 0x90, v0
	v_cvt_pk_bf16_f32 v179, v183, v179
	v_mad_i64_i32 v[182:183], s[0:1], v182, s47, v[134:135]
	v_cvt_pk_bf16_f32 v178, v178, v180
	v_cvt_pk_bf16_f32 v180, v181, v224
	v_cvt_pk_bf16_f32 v181, v227, v225
	v_lshl_add_u64 v[182:183], v[182:183], 0, v[136:137]
	global_store_dwordx4 v[182:183], v[178:181], off
	s_nop 1
	v_mul_f32_e32 v179, 0xbfb8aa3b, v30
	v_exp_f32_e32 v179, v179
	v_mul_f32_e32 v178, 0xbfb8aa3b, v38
	v_mul_f32_e32 v180, 0xbfb8aa3b, v39
	v_mul_f32_e32 v224, 0xbfb8aa3b, v40
	v_add_f32_e32 v179, 1.0, v179
	v_rcp_f32_e32 v181, v179
	v_mul_f32_e32 v179, 0xbfb8aa3b, v31
	v_exp_f32_e32 v179, v179
	v_mul_f32_e32 v226, 0xbfb8aa3b, v41
	v_mul_f32_e32 v227, 0xbfb8aa3b, v33
	v_exp_f32_e32 v178, v178
	v_add_f32_e32 v179, 1.0, v179
	v_rcp_f32_e32 v225, v179
	v_mul_f32_e32 v179, 0xbfb8aa3b, v32
	v_exp_f32_e32 v179, v179
	v_exp_f32_e32 v180, v180
	v_exp_f32_e32 v224, v224
	v_exp_f32_e32 v226, v226
	v_exp_f32_e32 v227, v227
	v_add_f32_e32 v179, 1.0, v179
	v_add_f32_e32 v178, 1.0, v178
	v_add_f32_e32 v180, 1.0, v180
	v_add_f32_e32 v224, 1.0, v224
	v_rcp_f32_e32 v239, v179
	v_add_f32_e32 v179, 1.0, v226
	v_add_f32_e32 v226, 1.0, v227
	v_rcp_f32_e32 v178, v178
	v_rcp_f32_e32 v180, v180
	v_rcp_f32_e32 v224, v224
	v_rcp_f32_e32 v179, v179
	v_rcp_f32_e32 v226, v226
	v_cvt_pk_bf16_f32 v178, v178, v180
	v_cvt_pk_bf16_f32 v180, v181, v225
	v_cvt_pk_bf16_f32 v179, v224, v179
	v_cvt_pk_bf16_f32 v181, v239, v226
	global_store_dwordx4 v[182:183], v[178:181], off offset:256
	s_nop 1
	v_mul_f32_e32 v179, 0xbfb8aa3b, v26
	v_exp_f32_e32 v179, v179
	v_mul_f32_e32 v183, 0xbfb8aa3b, v36
	v_mul_f32_e32 v225, 0xbfb8aa3b, v37
	v_mul_f32_e32 v178, 0xbfb8aa3b, v34
	v_add_f32_e32 v179, 1.0, v179
	v_rcp_f32_e32 v181, v179
	v_mul_f32_e32 v179, 0xbfb8aa3b, v27
	v_exp_f32_e32 v179, v179
	v_mul_f32_e32 v180, 0xbfb8aa3b, v35
	v_exp_f32_e32 v183, v183
	v_exp_f32_e32 v225, v225
	v_add_f32_e32 v179, 1.0, v179
	v_rcp_f32_e32 v224, v179
	v_mul_f32_e32 v179, 0xbfb8aa3b, v28
	v_exp_f32_e32 v179, v179
	v_mul_f32_e32 v226, 0xbfb8aa3b, v29
	v_exp_f32_e32 v178, v178
	v_exp_f32_e32 v180, v180
	v_exp_f32_e32 v226, v226
	v_add_f32_e32 v179, 1.0, v179
	v_add_f32_e32 v183, 1.0, v183
	v_rcp_f32_e32 v227, v179
	v_add_f32_e32 v179, 1.0, v225
	v_add_f32_e32 v178, 1.0, v178
	v_add_f32_e32 v180, 1.0, v180
	v_rcp_f32_e32 v183, v183
	v_rcp_f32_e32 v179, v179
	v_add_f32_e32 v225, 1.0, v226
	v_rcp_f32_e32 v178, v178
	v_rcp_f32_e32 v180, v180
	v_rcp_f32_e32 v225, v225
	v_add_u32_e32 v182, 0xa0, v0
	v_cvt_pk_bf16_f32 v179, v183, v179
	v_mad_i64_i32 v[182:183], s[0:1], v182, s47, v[134:135]
	v_cvt_pk_bf16_f32 v178, v178, v180
	v_cvt_pk_bf16_f32 v180, v181, v224
	v_cvt_pk_bf16_f32 v181, v227, v225
	v_lshl_add_u64 v[182:183], v[182:183], 0, v[136:137]
	global_store_dwordx4 v[182:183], v[178:181], off
	s_nop 1
	v_mul_f32_e32 v179, 0xbfb8aa3b, v14
	v_exp_f32_e32 v179, v179
	v_mul_f32_e32 v178, 0xbfb8aa3b, v22
	v_mul_f32_e32 v180, 0xbfb8aa3b, v23
	v_mul_f32_e32 v224, 0xbfb8aa3b, v24
	v_add_f32_e32 v179, 1.0, v179
	v_rcp_f32_e32 v181, v179
	v_mul_f32_e32 v179, 0xbfb8aa3b, v15
	v_exp_f32_e32 v179, v179
	v_mul_f32_e32 v226, 0xbfb8aa3b, v25
	v_mul_f32_e32 v227, 0xbfb8aa3b, v17
	v_exp_f32_e32 v178, v178
	v_add_f32_e32 v179, 1.0, v179
	v_rcp_f32_e32 v225, v179
	v_mul_f32_e32 v179, 0xbfb8aa3b, v16
	v_exp_f32_e32 v179, v179
	v_exp_f32_e32 v180, v180
	v_exp_f32_e32 v224, v224
	v_exp_f32_e32 v226, v226
	v_exp_f32_e32 v227, v227
	v_add_f32_e32 v179, 1.0, v179
	v_add_f32_e32 v178, 1.0, v178
	v_add_f32_e32 v180, 1.0, v180
	v_add_f32_e32 v224, 1.0, v224
	v_rcp_f32_e32 v239, v179
	v_add_f32_e32 v179, 1.0, v226
	v_add_f32_e32 v226, 1.0, v227
	v_rcp_f32_e32 v178, v178
	v_rcp_f32_e32 v180, v180
	v_rcp_f32_e32 v224, v224
	v_rcp_f32_e32 v179, v179
	v_rcp_f32_e32 v226, v226
	v_cvt_pk_bf16_f32 v178, v178, v180
	v_cvt_pk_bf16_f32 v180, v181, v225
	v_cvt_pk_bf16_f32 v179, v224, v179
	v_cvt_pk_bf16_f32 v181, v239, v226
	global_store_dwordx4 v[182:183], v[178:181], off offset:256
	s_nop 1
	v_mul_f32_e32 v179, 0xbfb8aa3b, v10
	v_exp_f32_e32 v179, v179
	v_mul_f32_e32 v180, 0xbfb8aa3b, v19
	v_mul_f32_e32 v181, 0xbfb8aa3b, v11
	v_exp_f32_e32 v180, v180
	v_exp_f32_e32 v181, v181
	v_add_f32_e32 v179, 1.0, v179
	v_rcp_f32_e32 v182, v179
	v_add_f32_e32 v179, 1.0, v180
	v_add_f32_e32 v180, 1.0, v181
	v_mul_f32_e32 v181, 0xbfb8aa3b, v20
	v_mul_f32_e32 v183, 0xbfb8aa3b, v12
	v_mul_f32_e32 v224, 0xbfb8aa3b, v21
	v_mul_f32_e32 v225, 0xbfb8aa3b, v13
	v_exp_f32_e32 v178, v228
	v_exp_f32_e32 v181, v181
	v_exp_f32_e32 v183, v183
	v_exp_f32_e32 v224, v224
	v_exp_f32_e32 v225, v225
	v_add_f32_e32 v178, 1.0, v178
	v_add_f32_e32 v181, 1.0, v181
	v_add_f32_e32 v183, 1.0, v183
	v_add_f32_e32 v224, 1.0, v224
	v_add_f32_e32 v225, 1.0, v225
	v_rcp_f32_e32 v178, v178
	v_rcp_f32_e32 v179, v179
	v_rcp_f32_e32 v180, v180
	v_rcp_f32_e32 v181, v181
	v_rcp_f32_e32 v183, v183
	v_rcp_f32_e32 v224, v224
	v_rcp_f32_e32 v225, v225
	v_add_u32_e32 v0, 0xb0, v0
	v_mad_i64_i32 v[134:135], s[0:1], v0, s47, v[134:135]
	v_cvt_pk_bf16_f32 v178, v178, v179
	v_cvt_pk_bf16_f32 v179, v181, v224
	v_cvt_pk_bf16_f32 v180, v182, v180
	v_cvt_pk_bf16_f32 v181, v183, v225
	v_lshl_add_u64 v[182:183], v[134:135], 0, v[136:137]
	global_store_dwordx4 v[182:183], v[178:181], off
	v_mul_f32_e32 v134, 0xbfb8aa3b, v2
	v_exp_f32_e32 v134, v134
	v_mul_f32_e32 v135, 0xbfb8aa3b, v7
	v_mul_f32_e32 v136, 0xbfb8aa3b, v3
	v_exp_f32_e32 v135, v135
	v_exp_f32_e32 v136, v136
	v_add_f32_e32 v134, 1.0, v134
	v_rcp_f32_e32 v137, v134
	v_add_f32_e32 v134, 1.0, v135
	v_add_f32_e32 v135, 1.0, v136
	v_mul_f32_e32 v136, 0xbfb8aa3b, v8
	v_mul_f32_e32 v178, 0xbfb8aa3b, v4
	v_exp_f32_e32 v136, v136
	v_exp_f32_e32 v178, v178
	v_mul_f32_e32 v0, 0xbfb8aa3b, v6
	v_rcp_f32_e32 v179, v135
	v_add_f32_e32 v135, 1.0, v136
	v_add_f32_e32 v136, 1.0, v178
	v_mul_f32_e32 v178, 0xbfb8aa3b, v9
	v_mul_f32_e32 v180, 0xbfb8aa3b, v5
	v_exp_f32_e32 v0, v0
	v_exp_f32_e32 v178, v178
	v_exp_f32_e32 v180, v180
	v_rcp_f32_e32 v181, v136
	v_add_f32_e32 v0, 1.0, v0
	v_add_f32_e32 v136, 1.0, v178
	v_add_f32_e32 v178, 1.0, v180
	v_rcp_f32_e32 v0, v0
	v_rcp_f32_e32 v134, v134
	v_rcp_f32_e32 v135, v135
	v_rcp_f32_e32 v136, v136
	v_rcp_f32_e32 v178, v178
	v_cvt_pk_bf16_f32 v134, v0, v134
	v_cvt_pk_bf16_f32 v135, v135, v136
	v_cvt_pk_bf16_f32 v136, v137, v179
	v_cvt_pk_bf16_f32 v137, v181, v178
	global_store_dwordx4 v[182:183], v[134:137], off offset:256
	s_mov_b64 s[0:1], 0

.LBB0_726:
	s_xor_b64 s[6:7], s[26:27], -1
	s_add_i32 vcc_lo, s14, 32
	s_lshl_b64 s[12:13], s[14:15], 7
	s_mov_b64 s[22:23], 0x1f00
	v_mov_b64_e32 v[130:131], v[158:159]
	v_mov_b64_e32 v[132:133], v[156:157]
	s_mov_b64 s[26:27], s[8:9]
	s_mov_b64 s[30:31], s[0:1]
	v_add_u32_e32 v224, 0x10000, v149
	v_add_u32_e32 v225, 0x14000, v149
	v_add_u32_e32 v226, 0x18000, v149
	v_add_u32_e32 v227, 0x1c000, v149
	s_branch .Lrot727_in

.Lrot727_in:
	s_add_i32 s14, s14, 2
	s_add_u32 s40, s30, s12
	s_addc_u32 s41, s31, s13
	s_add_u32 s84, s26, s12
	s_addc_u32 s85, s27, s13
	s_add_i32 s86, 0, 0x10000
	ds_read_b128 v[134:137], v224
	ds_read_b128 v[152:155], v224 offset:1024
	ds_read_b128 v[162:165], v224 offset:2048
	ds_read_b128 v[166:169], v224 offset:3072
	s_cmp_eq_u32 s12, s22
	s_cselect_b32 s61, s51, s41
	s_cselect_b32 s60, s50, s40
	s_cselect_b32 s41, s49, s85
	s_cselect_b32 s40, s80, s84
	v_lshl_add_u64 v[202:203], v[132:133], 0, s[12:13]
	s_add_i32 m0, s66, 0xc000
	ds_read_b128 v[170:173], v160
	ds_read_b128 v[174:177], v160 offset:1024
	ds_read_b128 v[178:181], v160 offset:2048
	ds_read_b128 v[182:185], v160 offset:3072
	ds_read_b128 v[186:189], v160 offset:4096
	ds_read_b128 v[190:193], v160 offset:5120
	ds_read_b128 v[194:197], v160 offset:6144
	ds_read_b128 v[198:201], v160 offset:7168
	global_load_lds_dwordx4 v[202:203], off
	v_lshl_add_u64 v[202:203], v[130:131], 0, s[12:13]
	s_add_i32 m0, s66, 0xe000
	s_nop 0
	global_load_lds_dwordx4 v[202:203], off
	s_waitcnt lgkmcnt(8)
	s_barrier
	s_waitcnt lgkmcnt(7)
	v_mfma_f32_16x16x32_bf16 v[126:129], v[134:137], v[170:173], v[126:129]
	v_mfma_f32_16x16x32_bf16 v[122:125], v[162:165], v[170:173], v[122:125]
	s_waitcnt lgkmcnt(5)
	v_mfma_f32_16x16x32_bf16 v[110:113], v[134:137], v[178:181], v[110:113]
	v_mfma_f32_16x16x32_bf16 v[106:109], v[162:165], v[178:181], v[106:109]
	s_waitcnt lgkmcnt(3)
	v_mfma_f32_16x16x32_bf16 v[94:97], v[134:137], v[186:189], v[94:97]
	v_mfma_f32_16x16x32_bf16 v[90:93], v[162:165], v[186:189], v[90:93]
	s_waitcnt lgkmcnt(1)
	v_mfma_f32_16x16x32_bf16 v[78:81], v[134:137], v[194:197], v[78:81]
	v_mfma_f32_16x16x32_bf16 v[74:77], v[162:165], v[194:197], v[74:77]
	v_mfma_f32_16x16x32_bf16 v[126:129], v[152:155], v[174:177], v[126:129]
	v_mfma_f32_16x16x32_bf16 v[122:125], v[166:169], v[174:177], v[122:125]
	v_mfma_f32_16x16x32_bf16 v[110:113], v[152:155], v[182:185], v[110:113]
	v_mfma_f32_16x16x32_bf16 v[106:109], v[166:169], v[182:185], v[106:109]
	v_mfma_f32_16x16x32_bf16 v[94:97], v[152:155], v[190:193], v[94:97]
	v_mfma_f32_16x16x32_bf16 v[90:93], v[166:169], v[190:193], v[90:93]
	s_waitcnt lgkmcnt(0)
	v_mfma_f32_16x16x32_bf16 v[78:81], v[152:155], v[198:201], v[78:81]
	v_mfma_f32_16x16x32_bf16 v[74:77], v[166:169], v[198:201], v[74:77]
	s_barrier
	s_add_i32 s87, 0, 0x14000
	s_add_i32 s84, s86, s65
	s_mov_b32 m0, s84
	ds_read_b128 v[202:205], v225
	ds_read_b128 v[206:209], v225 offset:1024
	ds_read_b128 v[216:219], v225 offset:2048
	global_load_lds_dwordx4 v0, s[40:41]
	s_add_i32 m0, s84, 0x2000
	ds_read_b128 v[220:223], v225 offset:3072
	global_load_lds_dwordx4 v138, s[40:41]
	s_barrier
	s_waitcnt lgkmcnt(3)
	v_mfma_f32_16x16x32_bf16 v[118:121], v[202:205], v[170:173], v[118:121]
	s_waitcnt lgkmcnt(1)
	v_mfma_f32_16x16x32_bf16 v[114:117], v[216:219], v[170:173], v[114:117]
	v_mfma_f32_16x16x32_bf16 v[102:105], v[202:205], v[178:181], v[102:105]
	v_mfma_f32_16x16x32_bf16 v[98:101], v[216:219], v[178:181], v[98:101]
	v_mfma_f32_16x16x32_bf16 v[86:89], v[202:205], v[186:189], v[86:89]
	v_mfma_f32_16x16x32_bf16 v[82:85], v[216:219], v[186:189], v[82:85]
	v_mfma_f32_16x16x32_bf16 v[70:73], v[202:205], v[194:197], v[70:73]
	v_mfma_f32_16x16x32_bf16 v[66:69], v[216:219], v[194:197], v[66:69]
	v_mfma_f32_16x16x32_bf16 v[118:121], v[206:209], v[174:177], v[118:121]
	s_waitcnt lgkmcnt(0)
	v_mfma_f32_16x16x32_bf16 v[114:117], v[220:223], v[174:177], v[114:117]
	v_mfma_f32_16x16x32_bf16 v[102:105], v[206:209], v[182:185], v[102:105]
	v_mfma_f32_16x16x32_bf16 v[98:101], v[220:223], v[182:185], v[98:101]
	v_mfma_f32_16x16x32_bf16 v[86:89], v[206:209], v[190:193], v[86:89]
	v_mfma_f32_16x16x32_bf16 v[82:85], v[220:223], v[190:193], v[82:85]
	v_mfma_f32_16x16x32_bf16 v[70:73], v[206:209], v[198:201], v[70:73]
	v_mfma_f32_16x16x32_bf16 v[66:69], v[220:223], v[198:201], v[66:69]
	s_mov_b32 m0, s66
	s_add_u32 s98, s60, 0x80
	s_addc_u32 s99, s61, 0
	s_barrier
	ds_read_b128 v[170:173], v160 offset:16384
	ds_read_b128 v[174:177], v160 offset:17408
	ds_read_b128 v[178:181], v160 offset:18432
	ds_read_b128 v[182:185], v160 offset:19456
	ds_read_b128 v[186:189], v160 offset:20480
	ds_read_b128 v[190:193], v160 offset:21504
	ds_read_b128 v[194:197], v160 offset:22528
	global_load_lds_dwordx4 v142, s[60:61]
	s_mov_b32 m0, s67
	ds_read_b128 v[198:201], v160 offset:23552
	global_load_lds_dwordx4 v140, s[60:61]
	s_barrier
	s_waitcnt lgkmcnt(7)
	v_mfma_f32_16x16x32_bf16 v[62:65], v[134:137], v[170:173], v[62:65]
	v_mfma_f32_16x16x32_bf16 v[58:61], v[162:165], v[170:173], v[58:61]
	s_waitcnt lgkmcnt(5)
	v_mfma_f32_16x16x32_bf16 v[46:49], v[134:137], v[178:181], v[46:49]
	v_mfma_f32_16x16x32_bf16 v[42:45], v[162:165], v[178:181], v[42:45]
	s_waitcnt lgkmcnt(3)
	v_mfma_f32_16x16x32_bf16 v[30:33], v[134:137], v[186:189], v[30:33]
	v_mfma_f32_16x16x32_bf16 v[26:29], v[162:165], v[186:189], v[26:29]
	s_waitcnt lgkmcnt(1)
	v_mfma_f32_16x16x32_bf16 v[14:17], v[134:137], v[194:197], v[14:17]
	v_mfma_f32_16x16x32_bf16 v[10:13], v[162:165], v[194:197], v[10:13]
	v_mfma_f32_16x16x32_bf16 v[62:65], v[152:155], v[174:177], v[62:65]
	v_mfma_f32_16x16x32_bf16 v[58:61], v[166:169], v[174:177], v[58:61]
	v_mfma_f32_16x16x32_bf16 v[46:49], v[152:155], v[182:185], v[46:49]
	v_mfma_f32_16x16x32_bf16 v[42:45], v[166:169], v[182:185], v[42:45]
	v_mfma_f32_16x16x32_bf16 v[30:33], v[152:155], v[190:193], v[30:33]
	v_mfma_f32_16x16x32_bf16 v[26:29], v[166:169], v[190:193], v[26:29]
	s_waitcnt lgkmcnt(0)
	v_mfma_f32_16x16x32_bf16 v[14:17], v[152:155], v[198:201], v[14:17]
	v_mfma_f32_16x16x32_bf16 v[10:13], v[166:169], v[198:201], v[10:13]
	s_barrier
	s_add_i32 s86, s87, s65
	s_mov_b32 m0, s86
	s_add_u32 s84, s40, 0x100000
	s_addc_u32 s85, s41, 0
	global_load_lds_dwordx4 v0, s[84:85]
	s_add_i32 m0, s86, 0x2000
	s_nop 0
	global_load_lds_dwordx4 v138, s[84:85]
	s_waitcnt vmcnt(6)
	s_barrier
	v_mfma_f32_16x16x32_bf16 v[54:57], v[202:205], v[170:173], v[54:57]
	v_mfma_f32_16x16x32_bf16 v[50:53], v[216:219], v[170:173], v[50:53]
	v_mfma_f32_16x16x32_bf16 v[38:41], v[202:205], v[178:181], v[38:41]
	v_mfma_f32_16x16x32_bf16 v[34:37], v[216:219], v[178:181], v[34:37]
	v_mfma_f32_16x16x32_bf16 v[22:25], v[202:205], v[186:189], v[22:25]
	v_mfma_f32_16x16x32_bf16 v[18:21], v[216:219], v[186:189], v[18:21]
	v_mfma_f32_16x16x32_bf16 v[6:9], v[202:205], v[194:197], v[6:9]
	v_mfma_f32_16x16x32_bf16 v[2:5], v[216:219], v[194:197], v[2:5]
	v_mfma_f32_16x16x32_bf16 v[54:57], v[206:209], v[174:177], v[54:57]
	v_mfma_f32_16x16x32_bf16 v[50:53], v[220:223], v[174:177], v[50:53]
	v_mfma_f32_16x16x32_bf16 v[38:41], v[206:209], v[182:185], v[38:41]
	v_mfma_f32_16x16x32_bf16 v[34:37], v[220:223], v[182:185], v[34:37]
	v_mfma_f32_16x16x32_bf16 v[22:25], v[206:209], v[190:193], v[22:25]
	v_mfma_f32_16x16x32_bf16 v[18:21], v[220:223], v[190:193], v[18:21]
	v_mfma_f32_16x16x32_bf16 v[6:9], v[206:209], v[198:201], v[6:9]
	v_mfma_f32_16x16x32_bf16 v[2:5], v[220:223], v[198:201], v[2:5]
	s_add_i32 s84, 0, 0x18000
	s_barrier
	ds_read_b128 v[134:137], v226
	ds_read_b128 v[152:155], v226 offset:1024
	ds_read_b128 v[162:165], v226 offset:2048
	ds_read_b128 v[166:169], v226 offset:3072
	s_add_u32 s60, s60, 0x100000
	s_addc_u32 s61, s61, 0
	s_mov_b32 m0, s68
	ds_read_b128 v[170:173], v160 offset:32768
	ds_read_b128 v[174:177], v160 offset:33792
	ds_read_b128 v[178:181], v160 offset:34816
	ds_read_b128 v[182:185], v160 offset:35840
	ds_read_b128 v[186:189], v160 offset:36864
	ds_read_b128 v[190:193], v160 offset:37888
	ds_read_b128 v[194:197], v160 offset:38912
	global_load_lds_dwordx4 v142, s[60:61]
	s_mov_b32 m0, s69
	ds_read_b128 v[198:201], v160 offset:39936
	global_load_lds_dwordx4 v140, s[60:61]
	s_waitcnt lgkmcnt(8)
	s_barrier
	s_waitcnt lgkmcnt(7)
	v_mfma_f32_16x16x32_bf16 v[126:129], v[134:137], v[170:173], v[126:129]
	v_mfma_f32_16x16x32_bf16 v[122:125], v[162:165], v[170:173], v[122:125]
	s_waitcnt lgkmcnt(5)
	v_mfma_f32_16x16x32_bf16 v[110:113], v[134:137], v[178:181], v[110:113]
	v_mfma_f32_16x16x32_bf16 v[106:109], v[162:165], v[178:181], v[106:109]
	s_waitcnt lgkmcnt(3)
	v_mfma_f32_16x16x32_bf16 v[94:97], v[134:137], v[186:189], v[94:97]
	v_mfma_f32_16x16x32_bf16 v[90:93], v[162:165], v[186:189], v[90:93]
	s_waitcnt lgkmcnt(1)
	v_mfma_f32_16x16x32_bf16 v[78:81], v[134:137], v[194:197], v[78:81]
	v_mfma_f32_16x16x32_bf16 v[74:77], v[162:165], v[194:197], v[74:77]
	v_mfma_f32_16x16x32_bf16 v[126:129], v[152:155], v[174:177], v[126:129]
	v_mfma_f32_16x16x32_bf16 v[122:125], v[166:169], v[174:177], v[122:125]
	v_mfma_f32_16x16x32_bf16 v[110:113], v[152:155], v[182:185], v[110:113]
	v_mfma_f32_16x16x32_bf16 v[106:109], v[166:169], v[182:185], v[106:109]
	v_mfma_f32_16x16x32_bf16 v[94:97], v[152:155], v[190:193], v[94:97]
	v_mfma_f32_16x16x32_bf16 v[90:93], v[166:169], v[190:193], v[90:93]
	s_waitcnt lgkmcnt(0)
	v_mfma_f32_16x16x32_bf16 v[78:81], v[152:155], v[198:201], v[78:81]
	v_mfma_f32_16x16x32_bf16 v[74:77], v[166:169], v[198:201], v[74:77]
	s_barrier
	s_add_i32 s60, 0, 0x1c000
	s_add_i32 s61, s84, s65
	s_add_u32 s100, s40, 0x80
	s_addc_u32 s101, s41, 0
	s_mov_b32 m0, s61
	ds_read_b128 v[202:205], v227
	ds_read_b128 v[206:209], v227 offset:1024
	ds_read_b128 v[216:219], v227 offset:2048
	global_load_lds_dwordx4 v0, s[100:101]
	s_add_i32 m0, s61, 0x2000
	ds_read_b128 v[220:223], v227 offset:3072
	global_load_lds_dwordx4 v138, s[100:101]
	s_barrier
	s_waitcnt lgkmcnt(3)
	v_mfma_f32_16x16x32_bf16 v[118:121], v[202:205], v[170:173], v[118:121]
	s_waitcnt lgkmcnt(1)
	v_mfma_f32_16x16x32_bf16 v[114:117], v[216:219], v[170:173], v[114:117]
	v_mfma_f32_16x16x32_bf16 v[102:105], v[202:205], v[178:181], v[102:105]
	v_mfma_f32_16x16x32_bf16 v[98:101], v[216:219], v[178:181], v[98:101]
	v_mfma_f32_16x16x32_bf16 v[86:89], v[202:205], v[186:189], v[86:89]
	v_mfma_f32_16x16x32_bf16 v[82:85], v[216:219], v[186:189], v[82:85]
	v_mfma_f32_16x16x32_bf16 v[70:73], v[202:205], v[194:197], v[70:73]
	v_mfma_f32_16x16x32_bf16 v[66:69], v[216:219], v[194:197], v[66:69]
	v_mfma_f32_16x16x32_bf16 v[118:121], v[206:209], v[174:177], v[118:121]
	s_waitcnt lgkmcnt(0)
	v_mfma_f32_16x16x32_bf16 v[114:117], v[220:223], v[174:177], v[114:117]
	v_mfma_f32_16x16x32_bf16 v[102:105], v[206:209], v[182:185], v[102:105]
	v_mfma_f32_16x16x32_bf16 v[98:101], v[220:223], v[182:185], v[98:101]
	v_mfma_f32_16x16x32_bf16 v[86:89], v[206:209], v[190:193], v[86:89]
	v_mfma_f32_16x16x32_bf16 v[82:85], v[220:223], v[190:193], v[82:85]
	v_mfma_f32_16x16x32_bf16 v[70:73], v[206:209], v[198:201], v[70:73]
	v_mfma_f32_16x16x32_bf16 v[66:69], v[220:223], v[198:201], v[66:69]
	s_mov_b32 m0, s76
	s_barrier
	ds_read_b128 v[170:173], v160 offset:49152
	ds_read_b128 v[174:177], v160 offset:50176
	ds_read_b128 v[178:181], v160 offset:51200
	ds_read_b128 v[182:185], v160 offset:52224
	ds_read_b128 v[186:189], v160 offset:53248
	ds_read_b128 v[190:193], v160 offset:54272
	ds_read_b128 v[194:197], v160 offset:55296
	global_load_lds_dwordx4 v142, s[98:99]
	s_mov_b32 m0, s77
	ds_read_b128 v[198:201], v160 offset:56320
	global_load_lds_dwordx4 v140, s[98:99]
	s_barrier
	s_waitcnt lgkmcnt(7)
	v_mfma_f32_16x16x32_bf16 v[62:65], v[134:137], v[170:173], v[62:65]
	v_mfma_f32_16x16x32_bf16 v[58:61], v[162:165], v[170:173], v[58:61]
	s_waitcnt lgkmcnt(5)
	v_mfma_f32_16x16x32_bf16 v[46:49], v[134:137], v[178:181], v[46:49]
	v_mfma_f32_16x16x32_bf16 v[42:45], v[162:165], v[178:181], v[42:45]
	s_waitcnt lgkmcnt(3)
	v_mfma_f32_16x16x32_bf16 v[30:33], v[134:137], v[186:189], v[30:33]
	v_mfma_f32_16x16x32_bf16 v[26:29], v[162:165], v[186:189], v[26:29]
	s_waitcnt lgkmcnt(1)
	v_mfma_f32_16x16x32_bf16 v[14:17], v[134:137], v[194:197], v[14:17]
	v_mfma_f32_16x16x32_bf16 v[10:13], v[162:165], v[194:197], v[10:13]
	v_mfma_f32_16x16x32_bf16 v[62:65], v[152:155], v[174:177], v[62:65]
	v_mfma_f32_16x16x32_bf16 v[58:61], v[166:169], v[174:177], v[58:61]
	v_mfma_f32_16x16x32_bf16 v[46:49], v[152:155], v[182:185], v[46:49]
	v_mfma_f32_16x16x32_bf16 v[42:45], v[166:169], v[182:185], v[42:45]
	v_mfma_f32_16x16x32_bf16 v[30:33], v[152:155], v[190:193], v[30:33]
	v_mfma_f32_16x16x32_bf16 v[26:29], v[166:169], v[190:193], v[26:29]
	s_waitcnt lgkmcnt(0)
	v_mfma_f32_16x16x32_bf16 v[14:17], v[152:155], v[198:201], v[14:17]
	v_mfma_f32_16x16x32_bf16 v[10:13], v[166:169], v[198:201], v[10:13]
	s_barrier
	s_add_i32 s60, s60, s65
	s_mov_b32 m0, s60
	s_add_u32 s40, s40, 0x100080
	s_addc_u32 s41, s41, 0
	global_load_lds_dwordx4 v0, s[40:41]
	s_add_i32 m0, s60, 0x2000
	s_nop 0
	global_load_lds_dwordx4 v138, s[40:41]
	s_waitcnt vmcnt(6)
	s_barrier
	v_mfma_f32_16x16x32_bf16 v[54:57], v[202:205], v[170:173], v[54:57]
	v_mfma_f32_16x16x32_bf16 v[50:53], v[216:219], v[170:173], v[50:53]
	v_mfma_f32_16x16x32_bf16 v[38:41], v[202:205], v[178:181], v[38:41]
	v_mfma_f32_16x16x32_bf16 v[34:37], v[216:219], v[178:181], v[34:37]
	v_mfma_f32_16x16x32_bf16 v[22:25], v[202:205], v[186:189], v[22:25]
	v_mfma_f32_16x16x32_bf16 v[18:21], v[216:219], v[186:189], v[18:21]
	v_mfma_f32_16x16x32_bf16 v[6:9], v[202:205], v[194:197], v[6:9]
	v_mfma_f32_16x16x32_bf16 v[2:5], v[216:219], v[194:197], v[2:5]
	v_mfma_f32_16x16x32_bf16 v[54:57], v[206:209], v[174:177], v[54:57]
	v_mfma_f32_16x16x32_bf16 v[50:53], v[220:223], v[174:177], v[50:53]
	v_mfma_f32_16x16x32_bf16 v[38:41], v[206:209], v[182:185], v[38:41]
	v_mfma_f32_16x16x32_bf16 v[34:37], v[220:223], v[182:185], v[34:37]
	v_mfma_f32_16x16x32_bf16 v[22:25], v[206:209], v[190:193], v[22:25]
	v_mfma_f32_16x16x32_bf16 v[18:21], v[220:223], v[190:193], v[18:21]
	v_mfma_f32_16x16x32_bf16 v[6:9], v[206:209], v[198:201], v[6:9]
	v_mfma_f32_16x16x32_bf16 v[2:5], v[220:223], v[198:201], v[2:5]
	s_add_u32 s30, s30, 0x100
	s_addc_u32 s31, s31, 0
	s_add_u32 s26, s26, 0x100
	s_addc_u32 s27, s27, 0
	s_add_u32 s22, s22, 0xffffff00
	s_addc_u32 s23, s23, -1
	v_lshl_add_u64 v[132:133], v[132:133], 0, s[18:19]
	s_cmp_ge_u32 s14, vcc_lo
	v_lshl_add_u64 v[130:131], v[130:131], 0, s[18:19]
	s_cbranch_scc0 .LBB0_727
	s_barrier
	s_mov_b32 s14, 32
	s_mov_b64 s[26:27], 0
	s_andn2_b64 vcc, exec, s[6:7]
	s_mov_b64 s[6:7], -1
	s_cbranch_vccnz .LBB0_724
	v_mov_b32_e32 v130, v148
	v_mov_b64_e32 v[134:135], s[38:39]
	v_and_or_b32 v132, v130, 15, s82
	v_lshrrev_b32_e32 v130, 1, v130
	v_and_or_b32 v130, v130, 24, s75
	v_or_b32_e32 v130, s81, v130
	s_mov_b32 s14, s48
	v_ashrrev_i32_e32 v131, 31, v130
	v_mad_i64_i32 v[136:137], s[0:1], v132, s47, v[134:135]
	v_lshlrev_b64 v[130:131], 1, v[130:131]
	v_lshl_add_u64 v[136:137], v[136:137], 0, v[130:131]
	v_add_co_u32_e32 v152, vcc, s72, v136
	v_ashrrev_i32_e32 v133, 31, v132
	s_nop 0
	v_addc_co_u32_e32 v153, vcc, 0, v137, vcc
	global_load_dwordx4 v[152:155], v[152:153], off
	v_lshlrev_b64 v[156:157], 12, v[132:133]
	v_lshl_add_u64 v[156:157], s[28:29], 0, v[156:157]
	v_lshl_add_u64 v[156:157], v[156:157], 0, v[130:131]
	v_lshl_add_u64 v[136:137], v[136:137], 0, s[34:35]
	s_mov_b32 s22, s79
	s_mov_b64 s[6:7], s[52:53]
	s_mov_b64 s[12:13], s[50:51]
	s_waitcnt vmcnt(0)
	v_lshlrev_b32_e32 v158, 16, v152
	v_and_b32_e32 v159, 0xffff0000, v152
	v_lshlrev_b32_e32 v152, 16, v153
	v_and_b32_e32 v153, 0xffff0000, v153
	v_lshlrev_b32_e32 v162, 16, v154
	v_and_b32_e32 v163, 0xffff0000, v154
	v_lshlrev_b32_e32 v154, 16, v155
	v_and_b32_e32 v155, 0xffff0000, v155
	v_pk_mul_f32 v[128:129], v[128:129], v[152:153]
	v_pk_mul_f32 v[126:127], v[126:127], v[158:159]
	v_pk_mul_f32 v[152:153], v[124:125], v[154:155]
	v_pk_mul_f32 v[124:125], v[122:123], v[162:163]
	v_cvt_pk_bf16_f32 v122, v126, v127
	v_cvt_pk_bf16_f32 v123, v128, v129
	v_cvt_pk_bf16_f32 v124, v124, v125
	v_cvt_pk_bf16_f32 v125, v152, v153
	global_store_dwordx4 v[156:157], v[122:125], off
	global_load_dwordx4 v[122:125], v[136:137], off offset:256
	v_add_u32_e32 v126, 16, v132
	v_mad_i64_i32 v[128:129], s[0:1], v126, s47, v[134:135]
	v_lshl_add_u64 v[128:129], v[128:129], 0, v[130:131]
	v_add_co_u32_e32 v136, vcc, s72, v128
	v_ashrrev_i32_e32 v127, 31, v126
	s_nop 0
	v_addc_co_u32_e32 v137, vcc, 0, v129, vcc
	s_waitcnt vmcnt(0)
	v_lshlrev_b32_e32 v152, 16, v122
	v_and_b32_e32 v153, 0xffff0000, v122
	v_lshlrev_b32_e32 v122, 16, v123
	v_and_b32_e32 v123, 0xffff0000, v123
	v_lshlrev_b32_e32 v154, 16, v124
	v_and_b32_e32 v155, 0xffff0000, v124
	v_lshlrev_b32_e32 v124, 16, v125
	v_and_b32_e32 v125, 0xffff0000, v125
	v_pk_mul_f32 v[120:121], v[120:121], v[122:123]
	v_pk_mul_f32 v[118:119], v[118:119], v[152:153]
	v_pk_mul_f32 v[122:123], v[116:117], v[124:125]
	v_pk_mul_f32 v[116:117], v[114:115], v[154:155]
	v_cvt_pk_bf16_f32 v114, v118, v119
	v_cvt_pk_bf16_f32 v115, v120, v121
	v_cvt_pk_bf16_f32 v116, v116, v117
	v_cvt_pk_bf16_f32 v117, v122, v123
	global_store_dwordx4 v[156:157], v[114:117], off offset:256
	global_load_dwordx4 v[114:117], v[136:137], off
	v_lshlrev_b64 v[118:119], 12, v[126:127]
	v_lshl_add_u64 v[118:119], s[28:29], 0, v[118:119]
	v_lshl_add_u64 v[118:119], v[118:119], 0, v[130:131]
	v_lshl_add_u64 v[120:121], v[128:129], 0, s[34:35]
	s_waitcnt vmcnt(0)
	v_lshlrev_b32_e32 v122, 16, v114
	v_and_b32_e32 v123, 0xffff0000, v114
	v_lshlrev_b32_e32 v114, 16, v115
	v_and_b32_e32 v115, 0xffff0000, v115
	v_lshlrev_b32_e32 v124, 16, v116
	v_and_b32_e32 v125, 0xffff0000, v116
	v_lshlrev_b32_e32 v116, 16, v117
	v_and_b32_e32 v117, 0xffff0000, v117
	v_pk_mul_f32 v[112:113], v[112:113], v[114:115]
	v_pk_mul_f32 v[110:111], v[110:111], v[122:123]
	v_pk_mul_f32 v[114:115], v[108:109], v[116:117]
	v_pk_mul_f32 v[108:109], v[106:107], v[124:125]
	v_cvt_pk_bf16_f32 v106, v110, v111
	v_cvt_pk_bf16_f32 v107, v112, v113
	v_cvt_pk_bf16_f32 v108, v108, v109
	v_cvt_pk_bf16_f32 v109, v114, v115
	global_store_dwordx4 v[118:119], v[106:109], off
	global_load_dwordx4 v[106:109], v[120:121], off offset:256
	v_add_u32_e32 v110, 32, v132
	v_mad_i64_i32 v[112:113], s[0:1], v110, s47, v[134:135]
	v_lshl_add_u64 v[112:113], v[112:113], 0, v[130:131]
	v_add_co_u32_e32 v114, vcc, s72, v112
	v_ashrrev_i32_e32 v111, 31, v110
	s_nop 0
	v_addc_co_u32_e32 v115, vcc, 0, v113, vcc
	s_waitcnt vmcnt(0)
	v_lshlrev_b32_e32 v116, 16, v106
	v_and_b32_e32 v117, 0xffff0000, v106
	v_lshlrev_b32_e32 v106, 16, v107
	v_and_b32_e32 v107, 0xffff0000, v107
	v_lshlrev_b32_e32 v120, 16, v108
	v_and_b32_e32 v121, 0xffff0000, v108
	v_lshlrev_b32_e32 v108, 16, v109
	v_and_b32_e32 v109, 0xffff0000, v109
	v_pk_mul_f32 v[104:105], v[104:105], v[106:107]
	v_pk_mul_f32 v[102:103], v[102:103], v[116:117]
	v_pk_mul_f32 v[106:107], v[100:101], v[108:109]
	v_pk_mul_f32 v[100:101], v[98:99], v[120:121]
	v_cvt_pk_bf16_f32 v98, v102, v103
	v_cvt_pk_bf16_f32 v99, v104, v105
	v_cvt_pk_bf16_f32 v100, v100, v101
	v_cvt_pk_bf16_f32 v101, v106, v107
	global_store_dwordx4 v[118:119], v[98:101], off offset:256
	global_load_dwordx4 v[98:101], v[114:115], off
	v_lshlrev_b64 v[102:103], 12, v[110:111]
	v_lshl_add_u64 v[102:103], s[28:29], 0, v[102:103]
	v_lshl_add_u64 v[102:103], v[102:103], 0, v[130:131]
	v_lshl_add_u64 v[104:105], v[112:113], 0, s[34:35]
	s_waitcnt vmcnt(0)
	v_lshlrev_b32_e32 v106, 16, v98
	v_and_b32_e32 v107, 0xffff0000, v98
	v_lshlrev_b32_e32 v98, 16, v99
	v_and_b32_e32 v99, 0xffff0000, v99
	v_lshlrev_b32_e32 v108, 16, v100
	v_and_b32_e32 v109, 0xffff0000, v100
	v_lshlrev_b32_e32 v100, 16, v101
	v_and_b32_e32 v101, 0xffff0000, v101
	v_pk_mul_f32 v[96:97], v[96:97], v[98:99]
	v_pk_mul_f32 v[94:95], v[94:95], v[106:107]
	v_pk_mul_f32 v[98:99], v[92:93], v[100:101]
	v_pk_mul_f32 v[92:93], v[90:91], v[108:109]
	v_cvt_pk_bf16_f32 v90, v94, v95
	v_cvt_pk_bf16_f32 v91, v96, v97
	v_cvt_pk_bf16_f32 v92, v92, v93
	v_cvt_pk_bf16_f32 v93, v98, v99
	global_store_dwordx4 v[102:103], v[90:93], off
	global_load_dwordx4 v[90:93], v[104:105], off offset:256
	v_add_u32_e32 v94, 48, v132
	v_mad_i64_i32 v[96:97], s[0:1], v94, s47, v[134:135]
	v_lshl_add_u64 v[96:97], v[96:97], 0, v[130:131]
	v_add_co_u32_e32 v98, vcc, s72, v96
	v_ashrrev_i32_e32 v95, 31, v94
	s_nop 0
	v_addc_co_u32_e32 v99, vcc, 0, v97, vcc
	s_waitcnt vmcnt(0)
	v_lshlrev_b32_e32 v100, 16, v90
	v_and_b32_e32 v101, 0xffff0000, v90
	v_lshlrev_b32_e32 v90, 16, v91
	v_and_b32_e32 v91, 0xffff0000, v91
	v_lshlrev_b32_e32 v104, 16, v92
	v_and_b32_e32 v105, 0xffff0000, v92
	v_lshlrev_b32_e32 v92, 16, v93
	v_and_b32_e32 v93, 0xffff0000, v93
	v_pk_mul_f32 v[88:89], v[88:89], v[90:91]
	v_pk_mul_f32 v[86:87], v[86:87], v[100:101]
	v_pk_mul_f32 v[90:91], v[84:85], v[92:93]
	v_pk_mul_f32 v[84:85], v[82:83], v[104:105]
	v_cvt_pk_bf16_f32 v82, v86, v87
	v_cvt_pk_bf16_f32 v83, v88, v89
	v_cvt_pk_bf16_f32 v84, v84, v85
	v_cvt_pk_bf16_f32 v85, v90, v91
	global_store_dwordx4 v[102:103], v[82:85], off offset:256
	global_load_dwordx4 v[82:85], v[98:99], off
	v_lshlrev_b64 v[86:87], 12, v[94:95]
	v_lshl_add_u64 v[86:87], s[28:29], 0, v[86:87]
	v_lshl_add_u64 v[86:87], v[86:87], 0, v[130:131]
	v_lshl_add_u64 v[88:89], v[96:97], 0, s[34:35]
	s_waitcnt vmcnt(0)
	v_lshlrev_b32_e32 v90, 16, v82
	v_and_b32_e32 v91, 0xffff0000, v82
	v_lshlrev_b32_e32 v82, 16, v83
	v_and_b32_e32 v83, 0xffff0000, v83
	v_lshlrev_b32_e32 v92, 16, v84
	v_and_b32_e32 v93, 0xffff0000, v84
	v_lshlrev_b32_e32 v84, 16, v85
	v_and_b32_e32 v85, 0xffff0000, v85
	v_pk_mul_f32 v[80:81], v[80:81], v[82:83]
	v_pk_mul_f32 v[78:79], v[78:79], v[90:91]
	v_pk_mul_f32 v[82:83], v[76:77], v[84:85]
	v_pk_mul_f32 v[76:77], v[74:75], v[92:93]
	v_cvt_pk_bf16_f32 v74, v78, v79
	v_cvt_pk_bf16_f32 v75, v80, v81
	v_cvt_pk_bf16_f32 v76, v76, v77
	v_cvt_pk_bf16_f32 v77, v82, v83
	global_store_dwordx4 v[86:87], v[74:77], off
	global_load_dwordx4 v[74:77], v[88:89], off offset:256
	v_add_u32_e32 v78, 0x80, v132
	v_mad_i64_i32 v[80:81], s[0:1], v78, s47, v[134:135]
	v_lshl_add_u64 v[80:81], v[80:81], 0, v[130:131]
	v_add_co_u32_e32 v82, vcc, s72, v80
	v_ashrrev_i32_e32 v79, 31, v78
	s_nop 0
	v_addc_co_u32_e32 v83, vcc, 0, v81, vcc
	s_waitcnt vmcnt(0)
	v_lshlrev_b32_e32 v84, 16, v74
	v_and_b32_e32 v85, 0xffff0000, v74
	v_lshlrev_b32_e32 v74, 16, v75
	v_and_b32_e32 v75, 0xffff0000, v75
	v_lshlrev_b32_e32 v88, 16, v76
	v_and_b32_e32 v89, 0xffff0000, v76
	v_lshlrev_b32_e32 v76, 16, v77
	v_and_b32_e32 v77, 0xffff0000, v77
	v_pk_mul_f32 v[72:73], v[72:73], v[74:75]
	v_pk_mul_f32 v[70:71], v[70:71], v[84:85]
	v_pk_mul_f32 v[74:75], v[68:69], v[76:77]
	v_pk_mul_f32 v[68:69], v[66:67], v[88:89]
	v_cvt_pk_bf16_f32 v66, v70, v71
	v_cvt_pk_bf16_f32 v67, v72, v73
	v_cvt_pk_bf16_f32 v68, v68, v69
	v_cvt_pk_bf16_f32 v69, v74, v75
	global_store_dwordx4 v[86:87], v[66:69], off offset:256
	global_load_dwordx4 v[66:69], v[82:83], off
	v_lshlrev_b64 v[70:71], 12, v[78:79]
	v_lshl_add_u64 v[70:71], s[28:29], 0, v[70:71]
	v_lshl_add_u64 v[70:71], v[70:71], 0, v[130:131]
	v_lshl_add_u64 v[72:73], v[80:81], 0, s[34:35]
	s_waitcnt vmcnt(0)
	v_lshlrev_b32_e32 v74, 16, v66
	v_and_b32_e32 v75, 0xffff0000, v66
	v_lshlrev_b32_e32 v66, 16, v67
	v_and_b32_e32 v67, 0xffff0000, v67
	v_lshlrev_b32_e32 v76, 16, v68
	v_and_b32_e32 v77, 0xffff0000, v68
	v_lshlrev_b32_e32 v68, 16, v69
	v_and_b32_e32 v69, 0xffff0000, v69
	v_pk_mul_f32 v[64:65], v[64:65], v[66:67]
	v_pk_mul_f32 v[62:63], v[62:63], v[74:75]
	v_pk_mul_f32 v[66:67], v[60:61], v[68:69]
	v_pk_mul_f32 v[60:61], v[58:59], v[76:77]
	v_cvt_pk_bf16_f32 v58, v62, v63
	v_cvt_pk_bf16_f32 v59, v64, v65
	v_cvt_pk_bf16_f32 v60, v60, v61
	v_cvt_pk_bf16_f32 v61, v66, v67
	global_store_dwordx4 v[70:71], v[58:61], off
	global_load_dwordx4 v[58:61], v[72:73], off offset:256
	v_add_u32_e32 v62, 0x90, v132
	v_mad_i64_i32 v[64:65], s[0:1], v62, s47, v[134:135]
	v_lshl_add_u64 v[64:65], v[64:65], 0, v[130:131]
	v_add_co_u32_e32 v66, vcc, s72, v64
	v_ashrrev_i32_e32 v63, 31, v62
	s_nop 0
	v_addc_co_u32_e32 v67, vcc, 0, v65, vcc
	s_waitcnt vmcnt(0)
	v_lshlrev_b32_e32 v68, 16, v58
	v_and_b32_e32 v69, 0xffff0000, v58
	v_lshlrev_b32_e32 v58, 16, v59
	v_and_b32_e32 v59, 0xffff0000, v59
	v_lshlrev_b32_e32 v72, 16, v60
	v_and_b32_e32 v73, 0xffff0000, v60
	v_lshlrev_b32_e32 v60, 16, v61
	v_and_b32_e32 v61, 0xffff0000, v61
	v_pk_mul_f32 v[56:57], v[56:57], v[58:59]
	v_pk_mul_f32 v[54:55], v[54:55], v[68:69]
	v_pk_mul_f32 v[58:59], v[52:53], v[60:61]
	v_pk_mul_f32 v[52:53], v[50:51], v[72:73]
	v_cvt_pk_bf16_f32 v50, v54, v55
	v_cvt_pk_bf16_f32 v51, v56, v57
	v_cvt_pk_bf16_f32 v52, v52, v53
	v_cvt_pk_bf16_f32 v53, v58, v59
	global_store_dwordx4 v[70:71], v[50:53], off offset:256
	global_load_dwordx4 v[50:53], v[66:67], off
	v_lshlrev_b64 v[54:55], 12, v[62:63]
	v_lshl_add_u64 v[54:55], s[28:29], 0, v[54:55]
	v_lshl_add_u64 v[54:55], v[54:55], 0, v[130:131]
	v_lshl_add_u64 v[56:57], v[64:65], 0, s[34:35]
	s_waitcnt vmcnt(0)
	v_lshlrev_b32_e32 v58, 16, v50
	v_and_b32_e32 v59, 0xffff0000, v50
	v_lshlrev_b32_e32 v50, 16, v51
	v_and_b32_e32 v51, 0xffff0000, v51
	v_lshlrev_b32_e32 v60, 16, v52
	v_and_b32_e32 v61, 0xffff0000, v52
	v_lshlrev_b32_e32 v52, 16, v53
	v_and_b32_e32 v53, 0xffff0000, v53
	v_pk_mul_f32 v[48:49], v[48:49], v[50:51]
	v_pk_mul_f32 v[46:47], v[46:47], v[58:59]
	v_pk_mul_f32 v[50:51], v[44:45], v[52:53]
	v_pk_mul_f32 v[44:45], v[42:43], v[60:61]
	v_cvt_pk_bf16_f32 v42, v46, v47
	v_cvt_pk_bf16_f32 v43, v48, v49
	v_cvt_pk_bf16_f32 v44, v44, v45
	v_cvt_pk_bf16_f32 v45, v50, v51
	global_store_dwordx4 v[54:55], v[42:45], off
	global_load_dwordx4 v[42:45], v[56:57], off offset:256
	v_add_u32_e32 v46, 0xa0, v132
	v_mad_i64_i32 v[48:49], s[0:1], v46, s47, v[134:135]
	v_lshl_add_u64 v[48:49], v[48:49], 0, v[130:131]
	v_add_co_u32_e32 v50, vcc, s72, v48
	v_ashrrev_i32_e32 v47, 31, v46
	s_nop 0
	v_addc_co_u32_e32 v51, vcc, 0, v49, vcc
	s_waitcnt vmcnt(0)
	v_lshlrev_b32_e32 v52, 16, v42
	v_and_b32_e32 v53, 0xffff0000, v42
	v_lshlrev_b32_e32 v42, 16, v43
	v_and_b32_e32 v43, 0xffff0000, v43
	v_lshlrev_b32_e32 v56, 16, v44
	v_and_b32_e32 v57, 0xffff0000, v44
	v_lshlrev_b32_e32 v44, 16, v45
	v_and_b32_e32 v45, 0xffff0000, v45
	v_pk_mul_f32 v[40:41], v[40:41], v[42:43]
	v_pk_mul_f32 v[38:39], v[38:39], v[52:53]
	v_pk_mul_f32 v[42:43], v[36:37], v[44:45]
	v_pk_mul_f32 v[36:37], v[34:35], v[56:57]
	v_cvt_pk_bf16_f32 v34, v38, v39
	v_cvt_pk_bf16_f32 v35, v40, v41
	v_cvt_pk_bf16_f32 v36, v36, v37
	v_cvt_pk_bf16_f32 v37, v42, v43
	global_store_dwordx4 v[54:55], v[34:37], off offset:256
	global_load_dwordx4 v[34:37], v[50:51], off
	v_lshlrev_b64 v[38:39], 12, v[46:47]
	v_lshl_add_u64 v[38:39], s[28:29], 0, v[38:39]
	v_lshl_add_u64 v[38:39], v[38:39], 0, v[130:131]
	v_lshl_add_u64 v[40:41], v[48:49], 0, s[34:35]
	s_waitcnt vmcnt(0)
	v_lshlrev_b32_e32 v42, 16, v34
	v_and_b32_e32 v43, 0xffff0000, v34
	v_lshlrev_b32_e32 v34, 16, v35
	v_and_b32_e32 v35, 0xffff0000, v35
	v_lshlrev_b32_e32 v44, 16, v36
	v_and_b32_e32 v45, 0xffff0000, v36
	v_lshlrev_b32_e32 v36, 16, v37
	v_and_b32_e32 v37, 0xffff0000, v37
	v_pk_mul_f32 v[32:33], v[32:33], v[34:35]
	v_pk_mul_f32 v[30:31], v[30:31], v[42:43]
	v_pk_mul_f32 v[34:35], v[28:29], v[36:37]
	v_pk_mul_f32 v[28:29], v[26:27], v[44:45]
	v_cvt_pk_bf16_f32 v26, v30, v31
	v_cvt_pk_bf16_f32 v27, v32, v33
	v_cvt_pk_bf16_f32 v28, v28, v29
	v_cvt_pk_bf16_f32 v29, v34, v35
	global_store_dwordx4 v[38:39], v[26:29], off
	global_load_dwordx4 v[26:29], v[40:41], off offset:256
	v_add_u32_e32 v30, 0xb0, v132
	v_mad_i64_i32 v[32:33], s[0:1], v30, s47, v[134:135]
	v_lshl_add_u64 v[32:33], v[32:33], 0, v[130:131]
	v_add_co_u32_e32 v34, vcc, s72, v32
	v_ashrrev_i32_e32 v31, 31, v30
	s_nop 0
	v_addc_co_u32_e32 v35, vcc, 0, v33, vcc
	s_and_b64 vcc, exec, s[36:37]
	s_waitcnt vmcnt(0)
	v_lshlrev_b32_e32 v36, 16, v26
	v_and_b32_e32 v37, 0xffff0000, v26
	v_lshlrev_b32_e32 v26, 16, v27
	v_and_b32_e32 v27, 0xffff0000, v27
	v_lshlrev_b32_e32 v40, 16, v28
	v_and_b32_e32 v41, 0xffff0000, v28
	v_lshlrev_b32_e32 v28, 16, v29
	v_and_b32_e32 v29, 0xffff0000, v29
	v_pk_mul_f32 v[24:25], v[24:25], v[26:27]
	v_pk_mul_f32 v[22:23], v[22:23], v[36:37]
	v_pk_mul_f32 v[26:27], v[20:21], v[28:29]
	v_pk_mul_f32 v[20:21], v[18:19], v[40:41]
	v_cvt_pk_bf16_f32 v18, v22, v23
	v_cvt_pk_bf16_f32 v19, v24, v25
	v_cvt_pk_bf16_f32 v20, v20, v21
	v_cvt_pk_bf16_f32 v21, v26, v27
	global_store_dwordx4 v[38:39], v[18:21], off offset:256
	global_load_dwordx4 v[18:21], v[34:35], off
	v_lshlrev_b64 v[22:23], 12, v[30:31]
	v_lshl_add_u64 v[22:23], s[28:29], 0, v[22:23]
	v_lshl_add_u64 v[22:23], v[22:23], 0, v[130:131]
	v_lshl_add_u64 v[24:25], v[32:33], 0, s[34:35]
	s_waitcnt vmcnt(0)
	v_lshlrev_b32_e32 v26, 16, v18
	v_and_b32_e32 v27, 0xffff0000, v18
	v_lshlrev_b32_e32 v18, 16, v19
	v_and_b32_e32 v19, 0xffff0000, v19
	v_lshlrev_b32_e32 v28, 16, v20
	v_and_b32_e32 v29, 0xffff0000, v20
	v_lshlrev_b32_e32 v20, 16, v21
	v_and_b32_e32 v21, 0xffff0000, v21
	v_pk_mul_f32 v[16:17], v[16:17], v[18:19]
	v_pk_mul_f32 v[14:15], v[14:15], v[26:27]
	v_pk_mul_f32 v[18:19], v[12:13], v[20:21]
	v_pk_mul_f32 v[12:13], v[10:11], v[28:29]
	v_cvt_pk_bf16_f32 v10, v14, v15
	v_cvt_pk_bf16_f32 v11, v16, v17
	v_cvt_pk_bf16_f32 v12, v12, v13
	v_cvt_pk_bf16_f32 v13, v18, v19
	global_store_dwordx4 v[22:23], v[10:13], off
	global_load_dwordx4 v[10:13], v[24:25], off offset:256
	s_waitcnt vmcnt(0)
	v_lshlrev_b32_e32 v14, 16, v10
	v_and_b32_e32 v15, 0xffff0000, v10
	v_lshlrev_b32_e32 v10, 16, v11
	v_and_b32_e32 v11, 0xffff0000, v11
	v_lshlrev_b32_e32 v16, 16, v12
	v_and_b32_e32 v17, 0xffff0000, v12
	v_lshlrev_b32_e32 v12, 16, v13
	v_and_b32_e32 v13, 0xffff0000, v13
	v_pk_mul_f32 v[8:9], v[8:9], v[10:11]
	v_pk_mul_f32 v[6:7], v[6:7], v[14:15]
	v_pk_mul_f32 v[10:11], v[4:5], v[12:13]
	v_pk_mul_f32 v[4:5], v[2:3], v[16:17]
	v_cvt_pk_bf16_f32 v2, v6, v7
	v_cvt_pk_bf16_f32 v3, v8, v9
	v_cvt_pk_bf16_f32 v4, v4, v5
	v_cvt_pk_bf16_f32 v5, v10, v11
	global_store_dwordx4 v[22:23], v[2:5], off offset:256
	s_cbranch_vccz .LBB0_715
	s_waitcnt vmcnt(0)
	s_cmpk_gt_u32 s97, 0xff
	s_cbranch_scc1 .LBB0_732
	s_barrier

.LBB0_806:
	s_add_u32 s79, s26, 0x100
	s_addc_u32 s80, s27, 0
	s_ashr_i32 s9, s8, 31
	s_lshl_b64 s[12:13], s[8:9], 20
	s_add_u32 s12, s38, s12
	s_addc_u32 s13, s39, s13
	s_and_b64 s[30:31], s[44:45], exec
	s_cselect_b32 s9, s13, s27
	s_cselect_b32 s44, s12, s26
	s_add_u32 s26, s6, 0x80080
	s_addc_u32 s27, s7, 0
	v_lshl_add_u64 v[140:141], s[26:27], 0, v[136:137]
	v_lshl_add_u64 v[142:143], s[26:27], 0, v[138:139]
	s_mov_b32 s45, -2
	s_mov_b64 s[26:27], 0
	v_add_u32_e32 v224, 0x10000, v144
	v_add_u32_e32 v225, 0x14000, v144
	v_add_u32_e32 v226, 0x18000, v144
	v_add_u32_e32 v227, 0x1c000, v144
	s_branch .Lrot807_in

.Lrot807_in:
	s_add_u32 s30, s6, s26
	s_addc_u32 s31, s7, s27
	s_add_u32 s30, s30, 0x100
	s_addc_u32 s31, s31, 0
	s_add_u32 s81, s79, s26
	s_addc_u32 s82, s80, s27
	s_add_i32 s83, 0, 0x10000
	ds_read_b128 v[152:155], v224
	ds_read_b128 v[156:159], v224 offset:1024
	ds_read_b128 v[160:163], v224 offset:2048
	ds_read_b128 v[164:167], v224 offset:3072
	s_cmpk_eq_i32 s26, 0xf00
	s_cselect_b32 s41, s23, s31
	s_cselect_b32 s40, s22, s30
	s_cselect_b32 s31, s9, s82
	s_cselect_b32 s30, s44, s81
	v_lshl_add_u64 v[146:147], v[140:141], 0, s[26:27]
	s_add_i32 m0, s61, 0xc000
	ds_read_b128 v[168:171], v145
	ds_read_b128 v[172:175], v145 offset:1024
	ds_read_b128 v[176:179], v145 offset:2048
	ds_read_b128 v[180:183], v145 offset:3072
	ds_read_b128 v[184:187], v145 offset:4096
	ds_read_b128 v[188:191], v145 offset:5120
	ds_read_b128 v[192:195], v145 offset:6144
	ds_read_b128 v[196:199], v145 offset:7168
	global_load_lds_dwordx4 v[146:147], off
	v_lshl_add_u64 v[146:147], v[142:143], 0, s[26:27]
	s_add_i32 m0, s61, 0xe000
	s_nop 0
	global_load_lds_dwordx4 v[146:147], off
	s_waitcnt lgkmcnt(8)
	s_barrier
	s_waitcnt lgkmcnt(7)
	v_mfma_f32_16x16x32_bf16 v[126:129], v[152:155], v[168:171], v[126:129]
	v_mfma_f32_16x16x32_bf16 v[122:125], v[160:163], v[168:171], v[122:125]
	s_waitcnt lgkmcnt(5)
	v_mfma_f32_16x16x32_bf16 v[110:113], v[152:155], v[176:179], v[110:113]
	v_mfma_f32_16x16x32_bf16 v[106:109], v[160:163], v[176:179], v[106:109]
	s_waitcnt lgkmcnt(3)
	v_mfma_f32_16x16x32_bf16 v[94:97], v[152:155], v[184:187], v[94:97]
	v_mfma_f32_16x16x32_bf16 v[90:93], v[160:163], v[184:187], v[90:93]
	s_waitcnt lgkmcnt(1)
	v_mfma_f32_16x16x32_bf16 v[78:81], v[152:155], v[192:195], v[78:81]
	v_mfma_f32_16x16x32_bf16 v[74:77], v[160:163], v[192:195], v[74:77]
	v_mfma_f32_16x16x32_bf16 v[126:129], v[156:159], v[172:175], v[126:129]
	v_mfma_f32_16x16x32_bf16 v[122:125], v[164:167], v[172:175], v[122:125]
	v_mfma_f32_16x16x32_bf16 v[110:113], v[156:159], v[180:183], v[110:113]
	v_mfma_f32_16x16x32_bf16 v[106:109], v[164:167], v[180:183], v[106:109]
	v_mfma_f32_16x16x32_bf16 v[94:97], v[156:159], v[188:191], v[94:97]
	v_mfma_f32_16x16x32_bf16 v[90:93], v[164:167], v[188:191], v[90:93]
	s_waitcnt lgkmcnt(0)
	v_mfma_f32_16x16x32_bf16 v[78:81], v[156:159], v[196:199], v[78:81]
	v_mfma_f32_16x16x32_bf16 v[74:77], v[164:167], v[196:199], v[74:77]
	s_barrier
	s_add_i32 s81, 0, 0x14000
	s_add_i32 s82, s83, s60
	ds_read_b128 v[200:203], v225
	ds_read_b128 v[204:207], v225 offset:1024
	ds_read_b128 v[216:219], v225 offset:2048
	ds_read_b128 v[220:223], v225 offset:3072
	s_mov_b32 m0, s82
	s_nop 0
	global_load_lds_dwordx4 v0, s[30:31]
	s_add_i32 m0, s82, 0x2000
	s_nop 0
	global_load_lds_dwordx4 v134, s[30:31]
	s_barrier
	s_waitcnt lgkmcnt(3)
	v_mfma_f32_16x16x32_bf16 v[118:121], v[200:203], v[168:171], v[118:121]
	s_waitcnt lgkmcnt(1)
	v_mfma_f32_16x16x32_bf16 v[114:117], v[216:219], v[168:171], v[114:117]
	v_mfma_f32_16x16x32_bf16 v[102:105], v[200:203], v[176:179], v[102:105]
	v_mfma_f32_16x16x32_bf16 v[98:101], v[216:219], v[176:179], v[98:101]
	v_mfma_f32_16x16x32_bf16 v[86:89], v[200:203], v[184:187], v[86:89]
	v_mfma_f32_16x16x32_bf16 v[82:85], v[216:219], v[184:187], v[82:85]
	v_mfma_f32_16x16x32_bf16 v[70:73], v[200:203], v[192:195], v[70:73]
	v_mfma_f32_16x16x32_bf16 v[66:69], v[216:219], v[192:195], v[66:69]
	v_mfma_f32_16x16x32_bf16 v[118:121], v[204:207], v[172:175], v[118:121]
	s_waitcnt lgkmcnt(0)
	v_mfma_f32_16x16x32_bf16 v[114:117], v[220:223], v[172:175], v[114:117]
	v_mfma_f32_16x16x32_bf16 v[102:105], v[204:207], v[180:183], v[102:105]
	v_mfma_f32_16x16x32_bf16 v[98:101], v[220:223], v[180:183], v[98:101]
	v_mfma_f32_16x16x32_bf16 v[86:89], v[204:207], v[188:191], v[86:89]
	v_mfma_f32_16x16x32_bf16 v[82:85], v[220:223], v[188:191], v[82:85]
	v_mfma_f32_16x16x32_bf16 v[70:73], v[204:207], v[196:199], v[70:73]
	v_mfma_f32_16x16x32_bf16 v[66:69], v[220:223], v[196:199], v[66:69]
	s_mov_b32 m0, s61
	s_add_u32 s98, s40, 0x80
	s_addc_u32 s99, s41, 0
	s_barrier
	ds_read_b128 v[168:171], v145 offset:16384
	ds_read_b128 v[172:175], v145 offset:17408
	ds_read_b128 v[176:179], v145 offset:18432
	ds_read_b128 v[180:183], v145 offset:19456
	ds_read_b128 v[184:187], v145 offset:20480
	ds_read_b128 v[188:191], v145 offset:21504
	ds_read_b128 v[192:195], v145 offset:22528
	global_load_lds_dwordx4 v0, s[40:41]
	s_mov_b32 m0, s64
	ds_read_b128 v[196:199], v145 offset:23552
	global_load_lds_dwordx4 v134, s[40:41]
	s_barrier
	s_waitcnt lgkmcnt(7)
	v_mfma_f32_16x16x32_bf16 v[62:65], v[152:155], v[168:171], v[62:65]
	v_mfma_f32_16x16x32_bf16 v[58:61], v[160:163], v[168:171], v[58:61]
	s_waitcnt lgkmcnt(5)
	v_mfma_f32_16x16x32_bf16 v[46:49], v[152:155], v[176:179], v[46:49]
	v_mfma_f32_16x16x32_bf16 v[42:45], v[160:163], v[176:179], v[42:45]
	s_waitcnt lgkmcnt(3)
	v_mfma_f32_16x16x32_bf16 v[30:33], v[152:155], v[184:187], v[30:33]
	v_mfma_f32_16x16x32_bf16 v[26:29], v[160:163], v[184:187], v[26:29]
	s_waitcnt lgkmcnt(1)
	v_mfma_f32_16x16x32_bf16 v[14:17], v[152:155], v[192:195], v[14:17]
	v_mfma_f32_16x16x32_bf16 v[10:13], v[160:163], v[192:195], v[10:13]
	v_mfma_f32_16x16x32_bf16 v[62:65], v[156:159], v[172:175], v[62:65]
	v_mfma_f32_16x16x32_bf16 v[58:61], v[164:167], v[172:175], v[58:61]
	v_mfma_f32_16x16x32_bf16 v[46:49], v[156:159], v[180:183], v[46:49]
	v_mfma_f32_16x16x32_bf16 v[42:45], v[164:167], v[180:183], v[42:45]
	v_mfma_f32_16x16x32_bf16 v[30:33], v[156:159], v[188:191], v[30:33]
	v_mfma_f32_16x16x32_bf16 v[26:29], v[164:167], v[188:191], v[26:29]
	s_waitcnt lgkmcnt(0)
	v_mfma_f32_16x16x32_bf16 v[14:17], v[156:159], v[196:199], v[14:17]
	v_mfma_f32_16x16x32_bf16 v[10:13], v[164:167], v[196:199], v[10:13]
	s_barrier
	s_add_i32 s81, s81, s60
	s_mov_b32 m0, s81
	s_add_u32 s82, s30, 0x80000
	s_addc_u32 s83, s31, 0
	global_load_lds_dwordx4 v0, s[82:83]
	s_add_i32 m0, s81, 0x2000
	s_nop 0
	global_load_lds_dwordx4 v134, s[82:83]
	s_waitcnt vmcnt(6)
	s_barrier
	v_mfma_f32_16x16x32_bf16 v[54:57], v[200:203], v[168:171], v[54:57]
	v_mfma_f32_16x16x32_bf16 v[50:53], v[216:219], v[168:171], v[50:53]
	v_mfma_f32_16x16x32_bf16 v[38:41], v[200:203], v[176:179], v[38:41]
	v_mfma_f32_16x16x32_bf16 v[34:37], v[216:219], v[176:179], v[34:37]
	v_mfma_f32_16x16x32_bf16 v[22:25], v[200:203], v[184:187], v[22:25]
	v_mfma_f32_16x16x32_bf16 v[18:21], v[216:219], v[184:187], v[18:21]
	v_mfma_f32_16x16x32_bf16 v[6:9], v[200:203], v[192:195], v[6:9]
	v_mfma_f32_16x16x32_bf16 v[2:5], v[216:219], v[192:195], v[2:5]
	v_mfma_f32_16x16x32_bf16 v[54:57], v[204:207], v[172:175], v[54:57]
	v_mfma_f32_16x16x32_bf16 v[50:53], v[220:223], v[172:175], v[50:53]
	v_mfma_f32_16x16x32_bf16 v[38:41], v[204:207], v[180:183], v[38:41]
	v_mfma_f32_16x16x32_bf16 v[34:37], v[220:223], v[180:183], v[34:37]
	v_mfma_f32_16x16x32_bf16 v[22:25], v[204:207], v[188:191], v[22:25]
	v_mfma_f32_16x16x32_bf16 v[18:21], v[220:223], v[188:191], v[18:21]
	v_mfma_f32_16x16x32_bf16 v[6:9], v[204:207], v[196:199], v[6:9]
	v_mfma_f32_16x16x32_bf16 v[2:5], v[220:223], v[196:199], v[2:5]
	s_add_i32 s81, 0, 0x18000
	s_barrier
	ds_read_b128 v[152:155], v226
	ds_read_b128 v[156:159], v226 offset:1024
	ds_read_b128 v[160:163], v226 offset:2048
	ds_read_b128 v[164:167], v226 offset:3072
	s_add_u32 s40, s40, 0x80000
	s_addc_u32 s41, s41, 0
	s_mov_b32 m0, s67
	ds_read_b128 v[168:171], v145 offset:32768
	ds_read_b128 v[172:175], v145 offset:33792
	ds_read_b128 v[176:179], v145 offset:34816
	ds_read_b128 v[180:183], v145 offset:35840
	ds_read_b128 v[184:187], v145 offset:36864
	ds_read_b128 v[188:191], v145 offset:37888
	ds_read_b128 v[192:195], v145 offset:38912
	global_load_lds_dwordx4 v0, s[40:41]
	s_mov_b32 m0, s68
	ds_read_b128 v[196:199], v145 offset:39936
	global_load_lds_dwordx4 v134, s[40:41]
	s_waitcnt lgkmcnt(8)
	s_barrier
	s_waitcnt lgkmcnt(7)
	v_mfma_f32_16x16x32_bf16 v[126:129], v[152:155], v[168:171], v[126:129]
	v_mfma_f32_16x16x32_bf16 v[122:125], v[160:163], v[168:171], v[122:125]
	s_waitcnt lgkmcnt(5)
	v_mfma_f32_16x16x32_bf16 v[110:113], v[152:155], v[176:179], v[110:113]
	v_mfma_f32_16x16x32_bf16 v[106:109], v[160:163], v[176:179], v[106:109]
	s_waitcnt lgkmcnt(3)
	v_mfma_f32_16x16x32_bf16 v[94:97], v[152:155], v[184:187], v[94:97]
	v_mfma_f32_16x16x32_bf16 v[90:93], v[160:163], v[184:187], v[90:93]
	s_waitcnt lgkmcnt(1)
	v_mfma_f32_16x16x32_bf16 v[78:81], v[152:155], v[192:195], v[78:81]
	v_mfma_f32_16x16x32_bf16 v[74:77], v[160:163], v[192:195], v[74:77]
	v_mfma_f32_16x16x32_bf16 v[126:129], v[156:159], v[172:175], v[126:129]
	v_mfma_f32_16x16x32_bf16 v[122:125], v[164:167], v[172:175], v[122:125]
	v_mfma_f32_16x16x32_bf16 v[110:113], v[156:159], v[180:183], v[110:113]
	v_mfma_f32_16x16x32_bf16 v[106:109], v[164:167], v[180:183], v[106:109]
	v_mfma_f32_16x16x32_bf16 v[94:97], v[156:159], v[188:191], v[94:97]
	v_mfma_f32_16x16x32_bf16 v[90:93], v[164:167], v[188:191], v[90:93]
	s_waitcnt lgkmcnt(0)
	v_mfma_f32_16x16x32_bf16 v[78:81], v[156:159], v[196:199], v[78:81]
	v_mfma_f32_16x16x32_bf16 v[74:77], v[164:167], v[196:199], v[74:77]
	s_barrier
	s_add_i32 s40, 0, 0x1c000
	s_add_i32 s41, s81, s60
	s_add_u32 s100, s30, 0x80
	s_addc_u32 s101, s31, 0
	s_mov_b32 m0, s41
	ds_read_b128 v[200:203], v227
	ds_read_b128 v[204:207], v227 offset:1024
	ds_read_b128 v[216:219], v227 offset:2048
	global_load_lds_dwordx4 v0, s[100:101]
	s_add_i32 m0, s41, 0x2000
	ds_read_b128 v[220:223], v227 offset:3072
	global_load_lds_dwordx4 v134, s[100:101]
	s_barrier
	s_waitcnt lgkmcnt(3)
	v_mfma_f32_16x16x32_bf16 v[118:121], v[200:203], v[168:171], v[118:121]
	s_waitcnt lgkmcnt(1)
	v_mfma_f32_16x16x32_bf16 v[114:117], v[216:219], v[168:171], v[114:117]
	v_mfma_f32_16x16x32_bf16 v[102:105], v[200:203], v[176:179], v[102:105]
	v_mfma_f32_16x16x32_bf16 v[98:101], v[216:219], v[176:179], v[98:101]
	v_mfma_f32_16x16x32_bf16 v[86:89], v[200:203], v[184:187], v[86:89]
	v_mfma_f32_16x16x32_bf16 v[82:85], v[216:219], v[184:187], v[82:85]
	v_mfma_f32_16x16x32_bf16 v[70:73], v[200:203], v[192:195], v[70:73]
	v_mfma_f32_16x16x32_bf16 v[66:69], v[216:219], v[192:195], v[66:69]
	v_mfma_f32_16x16x32_bf16 v[118:121], v[204:207], v[172:175], v[118:121]
	s_waitcnt lgkmcnt(0)
	v_mfma_f32_16x16x32_bf16 v[114:117], v[220:223], v[172:175], v[114:117]
	v_mfma_f32_16x16x32_bf16 v[102:105], v[204:207], v[180:183], v[102:105]
	v_mfma_f32_16x16x32_bf16 v[98:101], v[220:223], v[180:183], v[98:101]
	v_mfma_f32_16x16x32_bf16 v[86:89], v[204:207], v[188:191], v[86:89]
	v_mfma_f32_16x16x32_bf16 v[82:85], v[220:223], v[188:191], v[82:85]
	v_mfma_f32_16x16x32_bf16 v[70:73], v[204:207], v[196:199], v[70:73]
	v_mfma_f32_16x16x32_bf16 v[66:69], v[220:223], v[196:199], v[66:69]
	s_mov_b32 m0, s69
	s_barrier
	ds_read_b128 v[168:171], v145 offset:49152
	ds_read_b128 v[172:175], v145 offset:50176
	ds_read_b128 v[176:179], v145 offset:51200
	ds_read_b128 v[180:183], v145 offset:52224
	ds_read_b128 v[184:187], v145 offset:53248
	ds_read_b128 v[188:191], v145 offset:54272
	ds_read_b128 v[192:195], v145 offset:55296
	global_load_lds_dwordx4 v0, s[98:99]
	s_mov_b32 m0, s75
	ds_read_b128 v[196:199], v145 offset:56320
	global_load_lds_dwordx4 v134, s[98:99]
	s_barrier
	s_waitcnt lgkmcnt(7)
	v_mfma_f32_16x16x32_bf16 v[62:65], v[152:155], v[168:171], v[62:65]
	v_mfma_f32_16x16x32_bf16 v[58:61], v[160:163], v[168:171], v[58:61]
	s_waitcnt lgkmcnt(5)
	v_mfma_f32_16x16x32_bf16 v[46:49], v[152:155], v[176:179], v[46:49]
	v_mfma_f32_16x16x32_bf16 v[42:45], v[160:163], v[176:179], v[42:45]
	s_waitcnt lgkmcnt(3)
	v_mfma_f32_16x16x32_bf16 v[30:33], v[152:155], v[184:187], v[30:33]
	v_mfma_f32_16x16x32_bf16 v[26:29], v[160:163], v[184:187], v[26:29]
	s_waitcnt lgkmcnt(1)
	v_mfma_f32_16x16x32_bf16 v[14:17], v[152:155], v[192:195], v[14:17]
	v_mfma_f32_16x16x32_bf16 v[10:13], v[160:163], v[192:195], v[10:13]
	v_mfma_f32_16x16x32_bf16 v[62:65], v[156:159], v[172:175], v[62:65]
	v_mfma_f32_16x16x32_bf16 v[58:61], v[164:167], v[172:175], v[58:61]
	v_mfma_f32_16x16x32_bf16 v[46:49], v[156:159], v[180:183], v[46:49]
	v_mfma_f32_16x16x32_bf16 v[42:45], v[164:167], v[180:183], v[42:45]
	v_mfma_f32_16x16x32_bf16 v[30:33], v[156:159], v[188:191], v[30:33]
	v_mfma_f32_16x16x32_bf16 v[26:29], v[164:167], v[188:191], v[26:29]
	s_waitcnt lgkmcnt(0)
	v_mfma_f32_16x16x32_bf16 v[14:17], v[156:159], v[196:199], v[14:17]
	v_mfma_f32_16x16x32_bf16 v[10:13], v[164:167], v[196:199], v[10:13]
	s_barrier
	s_add_i32 s40, s40, s60
	s_mov_b32 m0, s40
	s_add_u32 s30, s30, 0x80080
	s_addc_u32 s31, s31, 0
	global_load_lds_dwordx4 v0, s[30:31]
	s_add_i32 m0, s40, 0x2000
	s_nop 0
	global_load_lds_dwordx4 v134, s[30:31]
	s_waitcnt vmcnt(6)
	s_barrier
	v_mfma_f32_16x16x32_bf16 v[54:57], v[200:203], v[168:171], v[54:57]
	v_mfma_f32_16x16x32_bf16 v[50:53], v[216:219], v[168:171], v[50:53]
	v_mfma_f32_16x16x32_bf16 v[38:41], v[200:203], v[176:179], v[38:41]
	v_mfma_f32_16x16x32_bf16 v[34:37], v[216:219], v[176:179], v[34:37]
	v_mfma_f32_16x16x32_bf16 v[22:25], v[200:203], v[184:187], v[22:25]
	v_mfma_f32_16x16x32_bf16 v[18:21], v[216:219], v[184:187], v[18:21]
	v_mfma_f32_16x16x32_bf16 v[6:9], v[200:203], v[192:195], v[6:9]
	v_mfma_f32_16x16x32_bf16 v[2:5], v[216:219], v[192:195], v[2:5]
	v_mfma_f32_16x16x32_bf16 v[54:57], v[204:207], v[172:175], v[54:57]
	v_mfma_f32_16x16x32_bf16 v[50:53], v[220:223], v[172:175], v[50:53]
	v_mfma_f32_16x16x32_bf16 v[38:41], v[204:207], v[180:183], v[38:41]
	v_mfma_f32_16x16x32_bf16 v[34:37], v[220:223], v[180:183], v[34:37]
	v_mfma_f32_16x16x32_bf16 v[22:25], v[204:207], v[188:191], v[22:25]
	v_mfma_f32_16x16x32_bf16 v[18:21], v[220:223], v[188:191], v[18:21]
	v_mfma_f32_16x16x32_bf16 v[6:9], v[204:207], v[196:199], v[6:9]
	v_mfma_f32_16x16x32_bf16 v[2:5], v[220:223], v[196:199], v[2:5]
	s_add_i32 s45, s45, 2
	s_add_u32 s26, s26, 0x100
	s_addc_u32 s27, s27, 0
	s_cmp_gt_u32 s45, 29
	s_cbranch_scc0 .LBB0_807
	s_barrier
	s_add_u32 s26, s79, 0xffffff00
	s_addc_u32 s27, s80, -1
	s_and_b64 vcc, exec, s[42:43]
	s_cbranch_vccnz .LBB0_796
	v_mov_b64_e32 v[2:3], 0
	s_mov_b32 s14, s8
	s_mov_b32 s50, s77
	s_mov_b64 s[6:7], s[22:23]
	s_mov_b32 s76, s78
	v_mov_b64_e32 v[4:5], 0
	v_mov_b64_e32 v[6:7], 0
	v_mov_b64_e32 v[8:9], 0
	v_mov_b64_e32 v[10:11], 0
	v_mov_b64_e32 v[12:13], 0
	v_mov_b64_e32 v[14:15], 0
	v_mov_b64_e32 v[16:17], 0
	v_mov_b64_e32 v[18:19], 0
	v_mov_b64_e32 v[20:21], 0
	v_mov_b64_e32 v[22:23], 0
	v_mov_b64_e32 v[24:25], 0
	v_mov_b64_e32 v[26:27], 0
	v_mov_b64_e32 v[28:29], 0
	v_mov_b64_e32 v[30:31], 0
	v_mov_b64_e32 v[32:33], 0
	v_mov_b64_e32 v[34:35], 0
	v_mov_b64_e32 v[36:37], 0
	v_mov_b64_e32 v[38:39], 0
	v_mov_b64_e32 v[40:41], 0
	v_mov_b64_e32 v[42:43], 0
	v_mov_b64_e32 v[44:45], 0
	v_mov_b64_e32 v[46:47], 0
	v_mov_b64_e32 v[48:49], 0
	v_mov_b64_e32 v[50:51], 0
	v_mov_b64_e32 v[52:53], 0
	v_mov_b64_e32 v[54:55], 0
	v_mov_b64_e32 v[56:57], 0
	v_mov_b64_e32 v[58:59], 0
	v_mov_b64_e32 v[60:61], 0
	v_mov_b64_e32 v[62:63], 0
	v_mov_b64_e32 v[64:65], 0
	v_mov_b64_e32 v[66:67], 0
	v_mov_b64_e32 v[68:69], 0
	v_mov_b64_e32 v[70:71], 0
	v_mov_b64_e32 v[72:73], 0
	v_mov_b64_e32 v[74:75], 0
	v_mov_b64_e32 v[76:77], 0
	v_mov_b64_e32 v[78:79], 0
	v_mov_b64_e32 v[80:81], 0
	v_mov_b64_e32 v[82:83], 0
	v_mov_b64_e32 v[84:85], 0
	v_mov_b64_e32 v[86:87], 0
	v_mov_b64_e32 v[88:89], 0
	v_mov_b64_e32 v[90:91], 0
	v_mov_b64_e32 v[92:93], 0
	v_mov_b64_e32 v[94:95], 0
	v_mov_b64_e32 v[96:97], 0
	v_mov_b64_e32 v[98:99], 0
	v_mov_b64_e32 v[100:101], 0
	v_mov_b64_e32 v[102:103], 0
	v_mov_b64_e32 v[104:105], 0
	v_mov_b64_e32 v[106:107], 0
	v_mov_b64_e32 v[108:109], 0
	v_mov_b64_e32 v[110:111], 0
	v_mov_b64_e32 v[112:113], 0
	v_mov_b64_e32 v[114:115], 0
	v_mov_b64_e32 v[116:117], 0
	v_mov_b64_e32 v[118:119], 0
	v_mov_b64_e32 v[120:121], 0
	v_mov_b64_e32 v[122:123], 0
	v_mov_b64_e32 v[124:125], 0
	v_mov_b64_e32 v[126:127], 0
	v_mov_b64_e32 v[128:129], 0
	s_andn2_b64 vcc, exec, s[0:1]
	s_cbranch_vccnz .LBB0_797

.LBB0_938:
	s_ashr_i32 s23, s22, 31
	s_lshl_b64 s[28:29], s[22:23], 20
	s_add_u32 s28, s8, s28
	s_addc_u32 s29, s9, s29
	s_and_b64 s[38:39], s[42:43], exec
	s_cselect_b32 s23, s29, s37
	s_cselect_b32 s42, s28, s36
	s_add_u32 s30, s30, 0x80080
	s_addc_u32 s31, s31, 0
	s_add_u32 s43, s36, 0x100
	v_mov_b64_e32 v[2:3], 0
	s_addc_u32 s67, s37, 0
	s_mov_b32 s68, -2
	v_mov_b64_e32 v[4:5], 0
	v_mov_b64_e32 v[6:7], 0
	v_mov_b64_e32 v[8:9], 0
	v_mov_b64_e32 v[10:11], 0
	v_mov_b64_e32 v[12:13], 0
	v_mov_b64_e32 v[14:15], 0
	v_mov_b64_e32 v[16:17], 0
	v_mov_b64_e32 v[18:19], 0
	v_mov_b64_e32 v[20:21], 0
	v_mov_b64_e32 v[22:23], 0
	v_mov_b64_e32 v[24:25], 0
	v_mov_b64_e32 v[26:27], 0
	v_mov_b64_e32 v[28:29], 0
	v_mov_b64_e32 v[30:31], 0
	v_mov_b64_e32 v[32:33], 0
	v_mov_b64_e32 v[34:35], 0
	v_mov_b64_e32 v[36:37], 0
	v_mov_b64_e32 v[38:39], 0
	v_mov_b64_e32 v[40:41], 0
	v_mov_b64_e32 v[42:43], 0
	v_mov_b64_e32 v[44:45], 0
	v_mov_b64_e32 v[46:47], 0
	v_mov_b64_e32 v[48:49], 0
	v_mov_b64_e32 v[50:51], 0
	v_mov_b64_e32 v[52:53], 0
	v_mov_b64_e32 v[54:55], 0
	v_mov_b64_e32 v[56:57], 0
	v_mov_b64_e32 v[58:59], 0
	v_mov_b64_e32 v[60:61], 0
	v_mov_b64_e32 v[62:63], 0
	v_mov_b64_e32 v[64:65], 0
	v_mov_b64_e32 v[66:67], 0
	v_mov_b64_e32 v[68:69], 0
	v_mov_b64_e32 v[70:71], 0
	v_mov_b64_e32 v[72:73], 0
	v_mov_b64_e32 v[74:75], 0
	v_mov_b64_e32 v[76:77], 0
	v_mov_b64_e32 v[78:79], 0
	v_mov_b64_e32 v[80:81], 0
	v_mov_b64_e32 v[82:83], 0
	v_mov_b64_e32 v[84:85], 0
	v_mov_b64_e32 v[86:87], 0
	v_mov_b64_e32 v[88:89], 0
	v_mov_b64_e32 v[90:91], 0
	v_mov_b64_e32 v[92:93], 0
	v_mov_b64_e32 v[94:95], 0
	v_mov_b64_e32 v[96:97], 0
	v_mov_b64_e32 v[98:99], 0
	v_mov_b64_e32 v[100:101], 0
	v_mov_b64_e32 v[102:103], 0
	v_mov_b64_e32 v[104:105], 0
	v_mov_b64_e32 v[106:107], 0
	v_mov_b64_e32 v[108:109], 0
	v_mov_b64_e32 v[110:111], 0
	v_mov_b64_e32 v[112:113], 0
	v_mov_b64_e32 v[114:115], 0
	v_mov_b64_e32 v[116:117], 0
	v_mov_b64_e32 v[118:119], 0
	v_mov_b64_e32 v[120:121], 0
	v_mov_b64_e32 v[122:123], 0
	v_mov_b64_e32 v[124:125], 0
	v_mov_b64_e32 v[126:127], 0
	v_mov_b64_e32 v[128:129], 0
	v_add_u32_e32 v224, 0x10000, v140
	v_add_u32_e32 v225, 0x14000, v140
	v_add_u32_e32 v226, 0x18000, v140
	v_add_u32_e32 v227, 0x1c000, v140
	s_branch .Lrot939_in

.Lrot939_in:
	s_add_u32 s36, s30, 0xfff80080
	s_addc_u32 s37, s31, -1
	s_add_i32 s69, 0, 0x10000
	ds_read_b128 v[142:145], v224
	ds_read_b128 v[152:155], v224 offset:1024
	ds_read_b128 v[156:159], v224 offset:2048
	ds_read_b128 v[160:163], v224 offset:3072
	s_cmp_eq_u32 s68, 28
	s_cselect_b32 s39, s27, s37
	s_cselect_b32 s38, s26, s36
	s_cselect_b32 s37, s23, s67
	s_cselect_b32 s36, s42, s43
	s_add_i32 m0, s41, 0xc000
	ds_read_b128 v[164:167], v141
	ds_read_b128 v[168:171], v141 offset:1024
	ds_read_b128 v[172:175], v141 offset:2048
	ds_read_b128 v[176:179], v141 offset:3072
	ds_read_b128 v[180:183], v141 offset:4096
	ds_read_b128 v[184:187], v141 offset:5120
	ds_read_b128 v[188:191], v141 offset:6144
	global_load_lds_dwordx4 v136, s[30:31]
	s_add_i32 m0, s41, 0xe000
	ds_read_b128 v[192:195], v141 offset:7168
	global_load_lds_dwordx4 v138, s[30:31]
	s_waitcnt lgkmcnt(8)
	s_barrier
	s_waitcnt lgkmcnt(7)
	v_mfma_f32_16x16x32_bf16 v[126:129], v[142:145], v[164:167], v[126:129]
	v_mfma_f32_16x16x32_bf16 v[122:125], v[156:159], v[164:167], v[122:125]
	s_waitcnt lgkmcnt(5)
	v_mfma_f32_16x16x32_bf16 v[118:121], v[142:145], v[172:175], v[118:121]
	v_mfma_f32_16x16x32_bf16 v[114:117], v[156:159], v[172:175], v[114:117]
	s_waitcnt lgkmcnt(3)
	v_mfma_f32_16x16x32_bf16 v[102:105], v[142:145], v[180:183], v[102:105]
	v_mfma_f32_16x16x32_bf16 v[98:101], v[156:159], v[180:183], v[98:101]
	s_waitcnt lgkmcnt(1)
	v_mfma_f32_16x16x32_bf16 v[86:89], v[142:145], v[188:191], v[86:89]
	v_mfma_f32_16x16x32_bf16 v[82:85], v[156:159], v[188:191], v[82:85]
	v_mfma_f32_16x16x32_bf16 v[126:129], v[152:155], v[168:171], v[126:129]
	v_mfma_f32_16x16x32_bf16 v[122:125], v[160:163], v[168:171], v[122:125]
	v_mfma_f32_16x16x32_bf16 v[118:121], v[152:155], v[176:179], v[118:121]
	v_mfma_f32_16x16x32_bf16 v[114:117], v[160:163], v[176:179], v[114:117]
	v_mfma_f32_16x16x32_bf16 v[102:105], v[152:155], v[184:187], v[102:105]
	v_mfma_f32_16x16x32_bf16 v[98:101], v[160:163], v[184:187], v[98:101]
	s_waitcnt lgkmcnt(0)
	v_mfma_f32_16x16x32_bf16 v[86:89], v[152:155], v[192:195], v[86:89]
	v_mfma_f32_16x16x32_bf16 v[82:85], v[160:163], v[192:195], v[82:85]
	s_barrier
	s_add_i32 s75, 0, 0x14000
	s_add_i32 s69, s69, s40
	ds_read_b128 v[196:199], v225
	ds_read_b128 v[200:203], v225 offset:1024
	ds_read_b128 v[204:207], v225 offset:2048
	ds_read_b128 v[216:219], v225 offset:3072
	s_mov_b32 m0, s69
	s_nop 0
	global_load_lds_dwordx4 v0, s[36:37]
	s_add_i32 m0, s69, 0x2000
	s_nop 0
	global_load_lds_dwordx4 v130, s[36:37]
	s_barrier
	s_waitcnt lgkmcnt(3)
	v_mfma_f32_16x16x32_bf16 v[110:113], v[196:199], v[164:167], v[110:113]
	s_waitcnt lgkmcnt(1)
	v_mfma_f32_16x16x32_bf16 v[106:109], v[204:207], v[164:167], v[106:109]
	v_mfma_f32_16x16x32_bf16 v[94:97], v[196:199], v[172:175], v[94:97]
	v_mfma_f32_16x16x32_bf16 v[90:93], v[204:207], v[172:175], v[90:93]
	v_mfma_f32_16x16x32_bf16 v[78:81], v[196:199], v[180:183], v[78:81]
	v_mfma_f32_16x16x32_bf16 v[74:77], v[204:207], v[180:183], v[74:77]
	v_mfma_f32_16x16x32_bf16 v[70:73], v[196:199], v[188:191], v[70:73]
	v_mfma_f32_16x16x32_bf16 v[66:69], v[204:207], v[188:191], v[66:69]
	v_mfma_f32_16x16x32_bf16 v[110:113], v[200:203], v[168:171], v[110:113]
	s_waitcnt lgkmcnt(0)
	v_mfma_f32_16x16x32_bf16 v[106:109], v[216:219], v[168:171], v[106:109]
	v_mfma_f32_16x16x32_bf16 v[94:97], v[200:203], v[176:179], v[94:97]
	v_mfma_f32_16x16x32_bf16 v[90:93], v[216:219], v[176:179], v[90:93]
	v_mfma_f32_16x16x32_bf16 v[78:81], v[200:203], v[184:187], v[78:81]
	v_mfma_f32_16x16x32_bf16 v[74:77], v[216:219], v[184:187], v[74:77]
	v_mfma_f32_16x16x32_bf16 v[70:73], v[200:203], v[192:195], v[70:73]
	v_mfma_f32_16x16x32_bf16 v[66:69], v[216:219], v[192:195], v[66:69]
	s_mov_b32 m0, s41
	s_add_u32 s98, s38, 0x80
	s_addc_u32 s99, s39, 0
	s_barrier
	ds_read_b128 v[164:167], v141 offset:16384
	ds_read_b128 v[168:171], v141 offset:17408
	ds_read_b128 v[172:175], v141 offset:18432
	ds_read_b128 v[176:179], v141 offset:19456
	ds_read_b128 v[180:183], v141 offset:20480
	ds_read_b128 v[184:187], v141 offset:21504
	ds_read_b128 v[188:191], v141 offset:22528
	global_load_lds_dwordx4 v134, s[38:39]
	s_mov_b32 m0, s44
	ds_read_b128 v[192:195], v141 offset:23552
	global_load_lds_dwordx4 v132, s[38:39]
	s_barrier
	s_waitcnt lgkmcnt(7)
	v_mfma_f32_16x16x32_bf16 v[62:65], v[142:145], v[164:167], v[62:65]
	v_mfma_f32_16x16x32_bf16 v[58:61], v[156:159], v[164:167], v[58:61]
	s_waitcnt lgkmcnt(5)
	v_mfma_f32_16x16x32_bf16 v[54:57], v[142:145], v[172:175], v[54:57]
	v_mfma_f32_16x16x32_bf16 v[50:53], v[156:159], v[172:175], v[50:53]
	s_waitcnt lgkmcnt(3)
	v_mfma_f32_16x16x32_bf16 v[38:41], v[142:145], v[180:183], v[38:41]
	v_mfma_f32_16x16x32_bf16 v[34:37], v[156:159], v[180:183], v[34:37]
	s_waitcnt lgkmcnt(1)
	v_mfma_f32_16x16x32_bf16 v[22:25], v[142:145], v[188:191], v[22:25]
	v_mfma_f32_16x16x32_bf16 v[18:21], v[156:159], v[188:191], v[18:21]
	v_mfma_f32_16x16x32_bf16 v[62:65], v[152:155], v[168:171], v[62:65]
	v_mfma_f32_16x16x32_bf16 v[58:61], v[160:163], v[168:171], v[58:61]
	v_mfma_f32_16x16x32_bf16 v[54:57], v[152:155], v[176:179], v[54:57]
	v_mfma_f32_16x16x32_bf16 v[50:53], v[160:163], v[176:179], v[50:53]
	v_mfma_f32_16x16x32_bf16 v[38:41], v[152:155], v[184:187], v[38:41]
	v_mfma_f32_16x16x32_bf16 v[34:37], v[160:163], v[184:187], v[34:37]
	s_waitcnt lgkmcnt(0)
	v_mfma_f32_16x16x32_bf16 v[22:25], v[152:155], v[192:195], v[22:25]
	v_mfma_f32_16x16x32_bf16 v[18:21], v[160:163], v[192:195], v[18:21]
	s_barrier
	s_add_i32 s69, s75, s40
	s_mov_b32 m0, s69
	s_add_u32 s76, s36, 0x80000
	s_addc_u32 s77, s37, 0
	global_load_lds_dwordx4 v0, s[76:77]
	s_add_i32 m0, s69, 0x2000
	s_nop 0
	global_load_lds_dwordx4 v130, s[76:77]
	s_waitcnt vmcnt(6)
	s_barrier
	v_mfma_f32_16x16x32_bf16 v[46:49], v[196:199], v[164:167], v[46:49]
	v_mfma_f32_16x16x32_bf16 v[42:45], v[204:207], v[164:167], v[42:45]
	v_mfma_f32_16x16x32_bf16 v[30:33], v[196:199], v[172:175], v[30:33]
	v_mfma_f32_16x16x32_bf16 v[26:29], v[204:207], v[172:175], v[26:29]
	v_mfma_f32_16x16x32_bf16 v[14:17], v[196:199], v[180:183], v[14:17]
	v_mfma_f32_16x16x32_bf16 v[10:13], v[204:207], v[180:183], v[10:13]
	v_mfma_f32_16x16x32_bf16 v[6:9], v[196:199], v[188:191], v[6:9]
	v_mfma_f32_16x16x32_bf16 v[2:5], v[204:207], v[188:191], v[2:5]
	v_mfma_f32_16x16x32_bf16 v[46:49], v[200:203], v[168:171], v[46:49]
	v_mfma_f32_16x16x32_bf16 v[42:45], v[216:219], v[168:171], v[42:45]
	v_mfma_f32_16x16x32_bf16 v[30:33], v[200:203], v[176:179], v[30:33]
	v_mfma_f32_16x16x32_bf16 v[26:29], v[216:219], v[176:179], v[26:29]
	v_mfma_f32_16x16x32_bf16 v[14:17], v[200:203], v[184:187], v[14:17]
	v_mfma_f32_16x16x32_bf16 v[10:13], v[216:219], v[184:187], v[10:13]
	v_mfma_f32_16x16x32_bf16 v[6:9], v[200:203], v[192:195], v[6:9]
	v_mfma_f32_16x16x32_bf16 v[2:5], v[216:219], v[192:195], v[2:5]
	s_add_i32 s69, 0, 0x18000
	s_barrier
	ds_read_b128 v[142:145], v226
	ds_read_b128 v[152:155], v226 offset:1024
	ds_read_b128 v[156:159], v226 offset:2048
	ds_read_b128 v[160:163], v226 offset:3072
	s_add_u32 s38, s38, 0x80000
	s_addc_u32 s39, s39, 0
	s_mov_b32 m0, s45
	ds_read_b128 v[164:167], v141 offset:32768
	ds_read_b128 v[168:171], v141 offset:33792
	ds_read_b128 v[172:175], v141 offset:34816
	ds_read_b128 v[176:179], v141 offset:35840
	ds_read_b128 v[180:183], v141 offset:36864
	ds_read_b128 v[184:187], v141 offset:37888
	ds_read_b128 v[188:191], v141 offset:38912
	global_load_lds_dwordx4 v134, s[38:39]
	s_mov_b32 m0, s50
	ds_read_b128 v[192:195], v141 offset:39936
	global_load_lds_dwordx4 v132, s[38:39]
	s_waitcnt lgkmcnt(8)
	s_barrier
	s_waitcnt lgkmcnt(7)
	v_mfma_f32_16x16x32_bf16 v[126:129], v[142:145], v[164:167], v[126:129]
	v_mfma_f32_16x16x32_bf16 v[122:125], v[156:159], v[164:167], v[122:125]
	s_waitcnt lgkmcnt(5)
	v_mfma_f32_16x16x32_bf16 v[118:121], v[142:145], v[172:175], v[118:121]
	v_mfma_f32_16x16x32_bf16 v[114:117], v[156:159], v[172:175], v[114:117]
	s_waitcnt lgkmcnt(3)
	v_mfma_f32_16x16x32_bf16 v[102:105], v[142:145], v[180:183], v[102:105]
	v_mfma_f32_16x16x32_bf16 v[98:101], v[156:159], v[180:183], v[98:101]
	s_waitcnt lgkmcnt(1)
	v_mfma_f32_16x16x32_bf16 v[86:89], v[142:145], v[188:191], v[86:89]
	v_mfma_f32_16x16x32_bf16 v[82:85], v[156:159], v[188:191], v[82:85]
	v_mfma_f32_16x16x32_bf16 v[126:129], v[152:155], v[168:171], v[126:129]
	v_mfma_f32_16x16x32_bf16 v[122:125], v[160:163], v[168:171], v[122:125]
	v_mfma_f32_16x16x32_bf16 v[118:121], v[152:155], v[176:179], v[118:121]
	v_mfma_f32_16x16x32_bf16 v[114:117], v[160:163], v[176:179], v[114:117]
	v_mfma_f32_16x16x32_bf16 v[102:105], v[152:155], v[184:187], v[102:105]
	v_mfma_f32_16x16x32_bf16 v[98:101], v[160:163], v[184:187], v[98:101]
	s_waitcnt lgkmcnt(0)
	v_mfma_f32_16x16x32_bf16 v[86:89], v[152:155], v[192:195], v[86:89]
	v_mfma_f32_16x16x32_bf16 v[82:85], v[160:163], v[192:195], v[82:85]
	s_barrier
	s_add_i32 s38, 0, 0x1c000
	s_add_i32 s39, s69, s40
	s_add_u32 s100, s36, 0x80
	s_addc_u32 s101, s37, 0
	s_mov_b32 m0, s39
	ds_read_b128 v[196:199], v227
	ds_read_b128 v[200:203], v227 offset:1024
	ds_read_b128 v[204:207], v227 offset:2048
	global_load_lds_dwordx4 v0, s[100:101]
	s_add_i32 m0, s39, 0x2000
	ds_read_b128 v[216:219], v227 offset:3072
	global_load_lds_dwordx4 v130, s[100:101]
	s_barrier
	s_waitcnt lgkmcnt(3)
	v_mfma_f32_16x16x32_bf16 v[110:113], v[196:199], v[164:167], v[110:113]
	s_waitcnt lgkmcnt(1)
	v_mfma_f32_16x16x32_bf16 v[106:109], v[204:207], v[164:167], v[106:109]
	v_mfma_f32_16x16x32_bf16 v[94:97], v[196:199], v[172:175], v[94:97]
	v_mfma_f32_16x16x32_bf16 v[90:93], v[204:207], v[172:175], v[90:93]
	v_mfma_f32_16x16x32_bf16 v[78:81], v[196:199], v[180:183], v[78:81]
	v_mfma_f32_16x16x32_bf16 v[74:77], v[204:207], v[180:183], v[74:77]
	v_mfma_f32_16x16x32_bf16 v[70:73], v[196:199], v[188:191], v[70:73]
	v_mfma_f32_16x16x32_bf16 v[66:69], v[204:207], v[188:191], v[66:69]
	v_mfma_f32_16x16x32_bf16 v[110:113], v[200:203], v[168:171], v[110:113]
	s_waitcnt lgkmcnt(0)
	v_mfma_f32_16x16x32_bf16 v[106:109], v[216:219], v[168:171], v[106:109]
	v_mfma_f32_16x16x32_bf16 v[94:97], v[200:203], v[176:179], v[94:97]
	v_mfma_f32_16x16x32_bf16 v[90:93], v[216:219], v[176:179], v[90:93]
	v_mfma_f32_16x16x32_bf16 v[78:81], v[200:203], v[184:187], v[78:81]
	v_mfma_f32_16x16x32_bf16 v[74:77], v[216:219], v[184:187], v[74:77]
	v_mfma_f32_16x16x32_bf16 v[70:73], v[200:203], v[192:195], v[70:73]
	v_mfma_f32_16x16x32_bf16 v[66:69], v[216:219], v[192:195], v[66:69]
	s_mov_b32 m0, s52
	s_barrier
	ds_read_b128 v[164:167], v141 offset:49152
	ds_read_b128 v[168:171], v141 offset:50176
	ds_read_b128 v[172:175], v141 offset:51200
	ds_read_b128 v[176:179], v141 offset:52224
	ds_read_b128 v[180:183], v141 offset:53248
	ds_read_b128 v[184:187], v141 offset:54272
	ds_read_b128 v[188:191], v141 offset:55296
	global_load_lds_dwordx4 v134, s[98:99]
	s_mov_b32 m0, s53
	ds_read_b128 v[192:195], v141 offset:56320
	global_load_lds_dwordx4 v132, s[98:99]
	s_barrier
	s_waitcnt lgkmcnt(7)
	v_mfma_f32_16x16x32_bf16 v[62:65], v[142:145], v[164:167], v[62:65]
	v_mfma_f32_16x16x32_bf16 v[58:61], v[156:159], v[164:167], v[58:61]
	s_waitcnt lgkmcnt(5)
	v_mfma_f32_16x16x32_bf16 v[54:57], v[142:145], v[172:175], v[54:57]
	v_mfma_f32_16x16x32_bf16 v[50:53], v[156:159], v[172:175], v[50:53]
	s_waitcnt lgkmcnt(3)
	v_mfma_f32_16x16x32_bf16 v[38:41], v[142:145], v[180:183], v[38:41]
	v_mfma_f32_16x16x32_bf16 v[34:37], v[156:159], v[180:183], v[34:37]
	s_waitcnt lgkmcnt(1)
	v_mfma_f32_16x16x32_bf16 v[22:25], v[142:145], v[188:191], v[22:25]
	v_mfma_f32_16x16x32_bf16 v[18:21], v[156:159], v[188:191], v[18:21]
	v_mfma_f32_16x16x32_bf16 v[62:65], v[152:155], v[168:171], v[62:65]
	v_mfma_f32_16x16x32_bf16 v[58:61], v[160:163], v[168:171], v[58:61]
	v_mfma_f32_16x16x32_bf16 v[54:57], v[152:155], v[176:179], v[54:57]
	v_mfma_f32_16x16x32_bf16 v[50:53], v[160:163], v[176:179], v[50:53]
	v_mfma_f32_16x16x32_bf16 v[38:41], v[152:155], v[184:187], v[38:41]
	v_mfma_f32_16x16x32_bf16 v[34:37], v[160:163], v[184:187], v[34:37]
	s_waitcnt lgkmcnt(0)
	v_mfma_f32_16x16x32_bf16 v[22:25], v[152:155], v[192:195], v[22:25]
	v_mfma_f32_16x16x32_bf16 v[18:21], v[160:163], v[192:195], v[18:21]
	s_barrier
	s_add_i32 s38, s38, s40
	s_mov_b32 m0, s38
	s_add_u32 s36, s36, 0x80080
	s_addc_u32 s37, s37, 0
	global_load_lds_dwordx4 v0, s[36:37]
	s_add_i32 m0, s38, 0x2000
	s_nop 0
	global_load_lds_dwordx4 v130, s[36:37]
	s_waitcnt vmcnt(6)
	s_barrier
	v_mfma_f32_16x16x32_bf16 v[46:49], v[196:199], v[164:167], v[46:49]
	v_mfma_f32_16x16x32_bf16 v[42:45], v[204:207], v[164:167], v[42:45]
	v_mfma_f32_16x16x32_bf16 v[30:33], v[196:199], v[172:175], v[30:33]
	v_mfma_f32_16x16x32_bf16 v[26:29], v[204:207], v[172:175], v[26:29]
	v_mfma_f32_16x16x32_bf16 v[14:17], v[196:199], v[180:183], v[14:17]
	v_mfma_f32_16x16x32_bf16 v[10:13], v[204:207], v[180:183], v[10:13]
	v_mfma_f32_16x16x32_bf16 v[6:9], v[196:199], v[188:191], v[6:9]
	v_mfma_f32_16x16x32_bf16 v[2:5], v[204:207], v[188:191], v[2:5]
	v_mfma_f32_16x16x32_bf16 v[46:49], v[200:203], v[168:171], v[46:49]
	v_mfma_f32_16x16x32_bf16 v[42:45], v[216:219], v[168:171], v[42:45]
	v_mfma_f32_16x16x32_bf16 v[30:33], v[200:203], v[176:179], v[30:33]
	v_mfma_f32_16x16x32_bf16 v[26:29], v[216:219], v[176:179], v[26:29]
	v_mfma_f32_16x16x32_bf16 v[14:17], v[200:203], v[184:187], v[14:17]
	v_mfma_f32_16x16x32_bf16 v[10:13], v[216:219], v[184:187], v[10:13]
	v_mfma_f32_16x16x32_bf16 v[6:9], v[200:203], v[192:195], v[6:9]
	v_mfma_f32_16x16x32_bf16 v[2:5], v[216:219], v[192:195], v[2:5]
	s_add_i32 s68, s68, 2
	s_add_u32 s30, s30, 0x100
	s_addc_u32 s31, s31, 0
	s_add_u32 s43, s43, 0x100
	s_addc_u32 s67, s67, 0
	s_cmp_gt_u32 s68, 29
	s_cbranch_scc0 .LBB0_939
	s_barrier
	s_lshr_b32 s23, s66, 3
	s_mulk_i32 s23, 0x880
	s_lshl_b32 s30, s66, 8
	v_mov_b32_e32 v142, v148
	s_and_b32 s30, s30, 0x700
	s_add_i32 s23, s60, s23
	s_add_i32 s23, s23, s30
	v_and_or_b32 v144, v142, 15, s23
	s_lshl_b32 s23, s65, 8
	v_lshrrev_b32_e32 v142, 1, v142
	v_and_or_b32 v142, v142, 24, s23
	v_or_b32_e32 v142, s51, v142
	v_cvt_pk_bf16_f32 v126, v126, v127
	v_cvt_pk_bf16_f32 v127, v128, v129
	v_cvt_pk_bf16_f32 v128, v122, v123
	v_mov_b64_e32 v[122:123], s[6:7]
	v_ashrrev_i32_e32 v143, 31, v142
	v_cvt_pk_bf16_f32 v70, v70, v71
	v_cvt_pk_bf16_f32 v71, v72, v73
	v_cvt_pk_bf16_f32 v72, v66, v67
	v_add_u32_e32 v66, 0x80, v144
	v_cvt_pk_bf16_f32 v129, v124, v125
	v_mad_i64_i32 v[124:125], s[30:31], v144, s74, v[122:123]
	v_lshlrev_b64 v[142:143], 1, v[142:143]
	v_cvt_pk_bf16_f32 v62, v62, v63
	v_cvt_pk_bf16_f32 v63, v64, v65
	v_cvt_pk_bf16_f32 v64, v58, v59
	v_mad_i64_i32 v[58:59], s[30:31], v66, s74, v[122:123]
	v_lshl_add_u64 v[124:125], v[124:125], 0, v[142:143]
	v_cvt_pk_bf16_f32 v110, v110, v111
	v_cvt_pk_bf16_f32 v111, v112, v113
	v_cvt_pk_bf16_f32 v112, v106, v107
	v_cvt_pk_bf16_f32 v113, v108, v109
	v_lshl_add_u64 v[58:59], v[58:59], 0, v[142:143]
	v_cvt_pk_bf16_f32 v46, v46, v47
	v_cvt_pk_bf16_f32 v47, v48, v49
	v_cvt_pk_bf16_f32 v48, v42, v43
	v_cvt_pk_bf16_f32 v49, v44, v45
	global_store_dwordx4 v[124:125], v[110:113], off offset:256
	global_store_dwordx4 v[58:59], v[46:49], off offset:256
	v_cvt_pk_bf16_f32 v94, v94, v95
	v_add_u32_e32 v110, 16, v144
	v_add_u32_e32 v46, 0x90, v144
	v_mad_i64_i32 v[110:111], s[30:31], v110, s74, v[122:123]
	v_mad_i64_i32 v[46:47], s[30:31], v46, s74, v[122:123]
	v_lshl_add_u64 v[110:111], v[110:111], 0, v[142:143]
	v_cvt_pk_bf16_f32 v95, v96, v97
	v_cvt_pk_bf16_f32 v96, v90, v91
	v_cvt_pk_bf16_f32 v97, v92, v93
	v_lshl_add_u64 v[46:47], v[46:47], 0, v[142:143]
	v_cvt_pk_bf16_f32 v30, v30, v31
	v_cvt_pk_bf16_f32 v31, v32, v33
	v_cvt_pk_bf16_f32 v32, v26, v27
	v_cvt_pk_bf16_f32 v33, v28, v29
	global_store_dwordx4 v[110:111], v[94:97], off offset:256
	global_store_dwordx4 v[46:47], v[30:33], off offset:256
	v_cvt_pk_bf16_f32 v78, v78, v79
	v_add_u32_e32 v94, 32, v144
	v_add_u32_e32 v30, 0xa0, v144
	v_mad_i64_i32 v[94:95], s[30:31], v94, s74, v[122:123]
	v_mad_i64_i32 v[30:31], s[30:31], v30, s74, v[122:123]
	v_lshl_add_u64 v[94:95], v[94:95], 0, v[142:143]
	v_cvt_pk_bf16_f32 v79, v80, v81
	v_cvt_pk_bf16_f32 v80, v74, v75
	v_cvt_pk_bf16_f32 v81, v76, v77
	v_lshl_add_u64 v[30:31], v[30:31], 0, v[142:143]
	v_cvt_pk_bf16_f32 v14, v14, v15
	v_cvt_pk_bf16_f32 v15, v16, v17
	v_cvt_pk_bf16_f32 v16, v10, v11
	v_cvt_pk_bf16_f32 v17, v12, v13
	global_store_dwordx4 v[94:95], v[78:81], off offset:256
	global_store_dwordx4 v[30:31], v[14:17], off offset:256
	v_cvt_pk_bf16_f32 v106, v118, v119
	v_add_u32_e32 v78, 48, v144
	v_add_u32_e32 v14, 0xb0, v144
	v_mad_i64_i32 v[78:79], s[30:31], v78, s74, v[122:123]
	v_mad_i64_i32 v[14:15], s[30:31], v14, s74, v[122:123]
	v_cvt_pk_bf16_f32 v107, v120, v121
	v_cvt_pk_bf16_f32 v108, v114, v115
	v_cvt_pk_bf16_f32 v109, v116, v117
	v_cvt_pk_bf16_f32 v90, v102, v103
	v_cvt_pk_bf16_f32 v91, v104, v105
	v_cvt_pk_bf16_f32 v92, v98, v99
	v_cvt_pk_bf16_f32 v93, v100, v101
	v_cvt_pk_bf16_f32 v74, v86, v87
	v_cvt_pk_bf16_f32 v75, v88, v89
	v_cvt_pk_bf16_f32 v76, v82, v83
	v_cvt_pk_bf16_f32 v77, v84, v85
	v_lshl_add_u64 v[78:79], v[78:79], 0, v[142:143]
	v_cvt_pk_bf16_f32 v73, v68, v69
	v_cvt_pk_bf16_f32 v65, v60, v61
	v_cvt_pk_bf16_f32 v42, v54, v55
	v_cvt_pk_bf16_f32 v43, v56, v57
	v_cvt_pk_bf16_f32 v44, v50, v51
	v_cvt_pk_bf16_f32 v45, v52, v53
	v_cvt_pk_bf16_f32 v26, v38, v39
	v_cvt_pk_bf16_f32 v27, v40, v41
	v_cvt_pk_bf16_f32 v28, v34, v35
	v_cvt_pk_bf16_f32 v29, v36, v37
	v_cvt_pk_bf16_f32 v10, v22, v23
	v_cvt_pk_bf16_f32 v11, v24, v25
	v_cvt_pk_bf16_f32 v12, v18, v19
	v_cvt_pk_bf16_f32 v13, v20, v21
	v_lshl_add_u64 v[14:15], v[14:15], 0, v[142:143]
	v_cvt_pk_bf16_f32 v6, v6, v7
	v_cvt_pk_bf16_f32 v7, v8, v9
	v_cvt_pk_bf16_f32 v8, v2, v3
	v_cvt_pk_bf16_f32 v9, v4, v5
	s_and_b64 vcc, exec, s[0:1]
	s_mov_b32 s65, s22
	s_mov_b32 s66, s64
	s_mov_b64 s[36:37], s[28:29]
	s_mov_b64 s[30:31], s[26:27]
	global_store_dwordx4 v[124:125], v[126:129], off
	global_store_dwordx4 v[110:111], v[106:109], off
	global_store_dwordx4 v[94:95], v[90:93], off
	global_store_dwordx4 v[78:79], v[74:77], off
	global_store_dwordx4 v[78:79], v[70:73], off offset:256
	global_store_dwordx4 v[58:59], v[62:65], off
	global_store_dwordx4 v[46:47], v[42:45], off
	global_store_dwordx4 v[30:31], v[26:29], off
	global_store_dwordx4 v[14:15], v[10:13], off
	global_store_dwordx4 v[14:15], v[6:9], off offset:256
	s_cbranch_vccz .LBB0_934
	s_waitcnt vmcnt(0)
	s_cmpk_gt_u32 s14, 0xff
	s_cbranch_scc1 .LBB0_943
	s_barrier

.LBB0_1083:
	s_add_u32 s42, s22, 0x100
	s_addc_u32 s43, s23, 0
	s_add_u32 s22, s6, 0x158080
	s_addc_u32 s23, s7, 0
	v_lshl_add_u64 v[142:143], s[22:23], 0, v[138:139]
	v_lshl_add_u64 v[144:145], s[22:23], 0, v[140:141]
	s_mov_b32 s78, -2
	s_mov_b64 s[22:23], 0
	v_add_u32_e32 v224, 0x10000, v146
	v_add_u32_e32 v225, 0x14000, v146
	v_add_u32_e32 v226, 0x18000, v146
	v_add_u32_e32 v227, 0x1c000, v146
	s_branch .Lrot1084_in

.Lrot1084_in:
	s_add_u32 s30, s6, s22
	s_addc_u32 s31, s7, s23
	s_add_u32 s30, s30, 0x100
	s_addc_u32 s31, s31, 0
	s_add_u32 s79, s42, s22
	s_addc_u32 s80, s43, s23
	s_add_i32 s81, 0, 0x10000
	ds_read_b128 v[152:155], v224
	ds_read_b128 v[156:159], v224 offset:1024
	ds_read_b128 v[160:163], v224 offset:2048
	ds_read_b128 v[164:167], v224 offset:3072
	s_cmpk_eq_i32 s22, 0x2a00
	s_cselect_b32 s41, s13, s31
	s_cselect_b32 s40, s12, s30
	s_cselect_b32 s31, s9, s80
	s_cselect_b32 s30, s8, s79
	v_lshl_add_u64 v[200:201], v[142:143], 0, s[22:23]
	s_add_i32 m0, s53, 0xc000
	ds_read_b128 v[168:171], v147
	ds_read_b128 v[172:175], v147 offset:1024
	ds_read_b128 v[176:179], v147 offset:2048
	ds_read_b128 v[180:183], v147 offset:3072
	ds_read_b128 v[184:187], v147 offset:4096
	ds_read_b128 v[188:191], v147 offset:5120
	ds_read_b128 v[192:195], v147 offset:6144
	ds_read_b128 v[196:199], v147 offset:7168
	global_load_lds_dwordx4 v[200:201], off
	v_lshl_add_u64 v[200:201], v[144:145], 0, s[22:23]
	s_add_i32 m0, s53, 0xe000
	s_nop 0
	global_load_lds_dwordx4 v[200:201], off
	s_waitcnt lgkmcnt(8)
	s_barrier
	s_waitcnt lgkmcnt(7)
	v_mfma_f32_16x16x32_bf16 v[126:129], v[152:155], v[168:171], v[126:129]
	v_mfma_f32_16x16x32_bf16 v[122:125], v[160:163], v[168:171], v[122:125]
	s_waitcnt lgkmcnt(5)
	v_mfma_f32_16x16x32_bf16 v[110:113], v[152:155], v[176:179], v[110:113]
	v_mfma_f32_16x16x32_bf16 v[106:109], v[160:163], v[176:179], v[106:109]
	s_waitcnt lgkmcnt(3)
	v_mfma_f32_16x16x32_bf16 v[94:97], v[152:155], v[184:187], v[94:97]
	v_mfma_f32_16x16x32_bf16 v[90:93], v[160:163], v[184:187], v[90:93]
	s_waitcnt lgkmcnt(1)
	v_mfma_f32_16x16x32_bf16 v[78:81], v[152:155], v[192:195], v[78:81]
	v_mfma_f32_16x16x32_bf16 v[74:77], v[160:163], v[192:195], v[74:77]
	v_mfma_f32_16x16x32_bf16 v[126:129], v[156:159], v[172:175], v[126:129]
	v_mfma_f32_16x16x32_bf16 v[122:125], v[164:167], v[172:175], v[122:125]
	v_mfma_f32_16x16x32_bf16 v[110:113], v[156:159], v[180:183], v[110:113]
	v_mfma_f32_16x16x32_bf16 v[106:109], v[164:167], v[180:183], v[106:109]
	v_mfma_f32_16x16x32_bf16 v[94:97], v[156:159], v[188:191], v[94:97]
	v_mfma_f32_16x16x32_bf16 v[90:93], v[164:167], v[188:191], v[90:93]
	s_waitcnt lgkmcnt(0)
	v_mfma_f32_16x16x32_bf16 v[78:81], v[156:159], v[196:199], v[78:81]
	v_mfma_f32_16x16x32_bf16 v[74:77], v[164:167], v[196:199], v[74:77]
	s_barrier
	s_add_i32 s79, 0, 0x14000
	s_add_i32 s80, s81, s52
	s_mov_b32 m0, s80
	ds_read_b128 v[200:203], v225
	ds_read_b128 v[204:207], v225 offset:1024
	ds_read_b128 v[216:219], v225 offset:2048
	global_load_lds_dwordx4 v0, s[30:31]
	s_add_i32 m0, s80, 0x2000
	ds_read_b128 v[220:223], v225 offset:3072
	global_load_lds_dwordx4 v136, s[30:31]
	s_barrier
	s_waitcnt lgkmcnt(3)
	v_mfma_f32_16x16x32_bf16 v[118:121], v[200:203], v[168:171], v[118:121]
	s_waitcnt lgkmcnt(1)
	v_mfma_f32_16x16x32_bf16 v[114:117], v[216:219], v[168:171], v[114:117]
	v_mfma_f32_16x16x32_bf16 v[102:105], v[200:203], v[176:179], v[102:105]
	v_mfma_f32_16x16x32_bf16 v[98:101], v[216:219], v[176:179], v[98:101]
	v_mfma_f32_16x16x32_bf16 v[86:89], v[200:203], v[184:187], v[86:89]
	v_mfma_f32_16x16x32_bf16 v[82:85], v[216:219], v[184:187], v[82:85]
	v_mfma_f32_16x16x32_bf16 v[70:73], v[200:203], v[192:195], v[70:73]
	v_mfma_f32_16x16x32_bf16 v[66:69], v[216:219], v[192:195], v[66:69]
	v_mfma_f32_16x16x32_bf16 v[118:121], v[204:207], v[172:175], v[118:121]
	s_waitcnt lgkmcnt(0)
	v_mfma_f32_16x16x32_bf16 v[114:117], v[220:223], v[172:175], v[114:117]
	v_mfma_f32_16x16x32_bf16 v[102:105], v[204:207], v[180:183], v[102:105]
	v_mfma_f32_16x16x32_bf16 v[98:101], v[220:223], v[180:183], v[98:101]
	v_mfma_f32_16x16x32_bf16 v[86:89], v[204:207], v[188:191], v[86:89]
	v_mfma_f32_16x16x32_bf16 v[82:85], v[220:223], v[188:191], v[82:85]
	v_mfma_f32_16x16x32_bf16 v[70:73], v[204:207], v[196:199], v[70:73]
	v_mfma_f32_16x16x32_bf16 v[66:69], v[220:223], v[196:199], v[66:69]
	s_mov_b32 m0, s53
	s_add_u32 s98, s40, 0x80
	s_addc_u32 s99, s41, 0
	s_barrier
	ds_read_b128 v[168:171], v147 offset:16384
	ds_read_b128 v[172:175], v147 offset:17408
	ds_read_b128 v[176:179], v147 offset:18432
	ds_read_b128 v[180:183], v147 offset:19456
	ds_read_b128 v[184:187], v147 offset:20480
	ds_read_b128 v[188:191], v147 offset:21504
	ds_read_b128 v[192:195], v147 offset:22528
	global_load_lds_dwordx4 v0, s[40:41]
	s_mov_b32 m0, s60
	ds_read_b128 v[196:199], v147 offset:23552
	global_load_lds_dwordx4 v136, s[40:41]
	s_barrier
	s_waitcnt lgkmcnt(7)
	v_mfma_f32_16x16x32_bf16 v[62:65], v[152:155], v[168:171], v[62:65]
	v_mfma_f32_16x16x32_bf16 v[58:61], v[160:163], v[168:171], v[58:61]
	s_waitcnt lgkmcnt(5)
	v_mfma_f32_16x16x32_bf16 v[46:49], v[152:155], v[176:179], v[46:49]
	v_mfma_f32_16x16x32_bf16 v[42:45], v[160:163], v[176:179], v[42:45]
	s_waitcnt lgkmcnt(3)
	v_mfma_f32_16x16x32_bf16 v[30:33], v[152:155], v[184:187], v[30:33]
	v_mfma_f32_16x16x32_bf16 v[26:29], v[160:163], v[184:187], v[26:29]
	s_waitcnt lgkmcnt(1)
	v_mfma_f32_16x16x32_bf16 v[14:17], v[152:155], v[192:195], v[14:17]
	v_mfma_f32_16x16x32_bf16 v[10:13], v[160:163], v[192:195], v[10:13]
	v_mfma_f32_16x16x32_bf16 v[62:65], v[156:159], v[172:175], v[62:65]
	v_mfma_f32_16x16x32_bf16 v[58:61], v[164:167], v[172:175], v[58:61]
	v_mfma_f32_16x16x32_bf16 v[46:49], v[156:159], v[180:183], v[46:49]
	v_mfma_f32_16x16x32_bf16 v[42:45], v[164:167], v[180:183], v[42:45]
	v_mfma_f32_16x16x32_bf16 v[30:33], v[156:159], v[188:191], v[30:33]
	v_mfma_f32_16x16x32_bf16 v[26:29], v[164:167], v[188:191], v[26:29]
	s_waitcnt lgkmcnt(0)
	v_mfma_f32_16x16x32_bf16 v[14:17], v[156:159], v[196:199], v[14:17]
	v_mfma_f32_16x16x32_bf16 v[10:13], v[164:167], v[196:199], v[10:13]
	s_barrier
	s_add_i32 s79, s79, s52
	s_mov_b32 m0, s79
	s_add_u32 s80, s30, 0x158000
	s_addc_u32 s81, s31, 0
	global_load_lds_dwordx4 v0, s[80:81]
	s_add_i32 m0, s79, 0x2000
	s_nop 0
	global_load_lds_dwordx4 v136, s[80:81]
	s_waitcnt vmcnt(6)
	s_barrier
	v_mfma_f32_16x16x32_bf16 v[54:57], v[200:203], v[168:171], v[54:57]
	v_mfma_f32_16x16x32_bf16 v[50:53], v[216:219], v[168:171], v[50:53]
	v_mfma_f32_16x16x32_bf16 v[38:41], v[200:203], v[176:179], v[38:41]
	v_mfma_f32_16x16x32_bf16 v[34:37], v[216:219], v[176:179], v[34:37]
	v_mfma_f32_16x16x32_bf16 v[22:25], v[200:203], v[184:187], v[22:25]
	v_mfma_f32_16x16x32_bf16 v[18:21], v[216:219], v[184:187], v[18:21]
	v_mfma_f32_16x16x32_bf16 v[6:9], v[200:203], v[192:195], v[6:9]
	v_mfma_f32_16x16x32_bf16 v[2:5], v[216:219], v[192:195], v[2:5]
	v_mfma_f32_16x16x32_bf16 v[54:57], v[204:207], v[172:175], v[54:57]
	v_mfma_f32_16x16x32_bf16 v[50:53], v[220:223], v[172:175], v[50:53]
	v_mfma_f32_16x16x32_bf16 v[38:41], v[204:207], v[180:183], v[38:41]
	v_mfma_f32_16x16x32_bf16 v[34:37], v[220:223], v[180:183], v[34:37]
	v_mfma_f32_16x16x32_bf16 v[22:25], v[204:207], v[188:191], v[22:25]
	v_mfma_f32_16x16x32_bf16 v[18:21], v[220:223], v[188:191], v[18:21]
	v_mfma_f32_16x16x32_bf16 v[6:9], v[204:207], v[196:199], v[6:9]
	v_mfma_f32_16x16x32_bf16 v[2:5], v[220:223], v[196:199], v[2:5]
	s_add_i32 s79, 0, 0x18000
	s_barrier
	ds_read_b128 v[152:155], v226
	ds_read_b128 v[156:159], v226 offset:1024
	ds_read_b128 v[160:163], v226 offset:2048
	ds_read_b128 v[164:167], v226 offset:3072
	s_add_u32 s40, s40, 0x158000
	s_addc_u32 s41, s41, 0
	s_mov_b32 m0, s65
	ds_read_b128 v[168:171], v147 offset:32768
	ds_read_b128 v[172:175], v147 offset:33792
	ds_read_b128 v[176:179], v147 offset:34816
	ds_read_b128 v[180:183], v147 offset:35840
	ds_read_b128 v[184:187], v147 offset:36864
	ds_read_b128 v[188:191], v147 offset:37888
	ds_read_b128 v[192:195], v147 offset:38912
	global_load_lds_dwordx4 v0, s[40:41]
	s_mov_b32 m0, s66
	ds_read_b128 v[196:199], v147 offset:39936
	global_load_lds_dwordx4 v136, s[40:41]
	s_waitcnt lgkmcnt(8)
	s_barrier
	s_waitcnt lgkmcnt(7)
	v_mfma_f32_16x16x32_bf16 v[126:129], v[152:155], v[168:171], v[126:129]
	v_mfma_f32_16x16x32_bf16 v[122:125], v[160:163], v[168:171], v[122:125]
	s_waitcnt lgkmcnt(5)
	v_mfma_f32_16x16x32_bf16 v[110:113], v[152:155], v[176:179], v[110:113]
	v_mfma_f32_16x16x32_bf16 v[106:109], v[160:163], v[176:179], v[106:109]
	s_waitcnt lgkmcnt(3)
	v_mfma_f32_16x16x32_bf16 v[94:97], v[152:155], v[184:187], v[94:97]
	v_mfma_f32_16x16x32_bf16 v[90:93], v[160:163], v[184:187], v[90:93]
	s_waitcnt lgkmcnt(1)
	v_mfma_f32_16x16x32_bf16 v[78:81], v[152:155], v[192:195], v[78:81]
	v_mfma_f32_16x16x32_bf16 v[74:77], v[160:163], v[192:195], v[74:77]
	v_mfma_f32_16x16x32_bf16 v[126:129], v[156:159], v[172:175], v[126:129]
	v_mfma_f32_16x16x32_bf16 v[122:125], v[164:167], v[172:175], v[122:125]
	v_mfma_f32_16x16x32_bf16 v[110:113], v[156:159], v[180:183], v[110:113]
	v_mfma_f32_16x16x32_bf16 v[106:109], v[164:167], v[180:183], v[106:109]
	v_mfma_f32_16x16x32_bf16 v[94:97], v[156:159], v[188:191], v[94:97]
	v_mfma_f32_16x16x32_bf16 v[90:93], v[164:167], v[188:191], v[90:93]
	s_waitcnt lgkmcnt(0)
	v_mfma_f32_16x16x32_bf16 v[78:81], v[156:159], v[196:199], v[78:81]
	v_mfma_f32_16x16x32_bf16 v[74:77], v[164:167], v[196:199], v[74:77]
	s_barrier
	s_add_i32 s40, 0, 0x1c000
	s_add_i32 s41, s79, s52
	s_add_u32 s100, s30, 0x80
	s_addc_u32 s101, s31, 0
	s_mov_b32 m0, s41
	ds_read_b128 v[200:203], v227
	ds_read_b128 v[204:207], v227 offset:1024
	ds_read_b128 v[216:219], v227 offset:2048
	global_load_lds_dwordx4 v0, s[100:101]
	s_add_i32 m0, s41, 0x2000
	ds_read_b128 v[220:223], v227 offset:3072
	global_load_lds_dwordx4 v136, s[100:101]
	s_barrier
	s_waitcnt lgkmcnt(3)
	v_mfma_f32_16x16x32_bf16 v[118:121], v[200:203], v[168:171], v[118:121]
	s_waitcnt lgkmcnt(1)
	v_mfma_f32_16x16x32_bf16 v[114:117], v[216:219], v[168:171], v[114:117]
	v_mfma_f32_16x16x32_bf16 v[102:105], v[200:203], v[176:179], v[102:105]
	v_mfma_f32_16x16x32_bf16 v[98:101], v[216:219], v[176:179], v[98:101]
	v_mfma_f32_16x16x32_bf16 v[86:89], v[200:203], v[184:187], v[86:89]
	v_mfma_f32_16x16x32_bf16 v[82:85], v[216:219], v[184:187], v[82:85]
	v_mfma_f32_16x16x32_bf16 v[70:73], v[200:203], v[192:195], v[70:73]
	v_mfma_f32_16x16x32_bf16 v[66:69], v[216:219], v[192:195], v[66:69]
	v_mfma_f32_16x16x32_bf16 v[118:121], v[204:207], v[172:175], v[118:121]
	s_waitcnt lgkmcnt(0)
	v_mfma_f32_16x16x32_bf16 v[114:117], v[220:223], v[172:175], v[114:117]
	v_mfma_f32_16x16x32_bf16 v[102:105], v[204:207], v[180:183], v[102:105]
	v_mfma_f32_16x16x32_bf16 v[98:101], v[220:223], v[180:183], v[98:101]
	v_mfma_f32_16x16x32_bf16 v[86:89], v[204:207], v[188:191], v[86:89]
	v_mfma_f32_16x16x32_bf16 v[82:85], v[220:223], v[188:191], v[82:85]
	v_mfma_f32_16x16x32_bf16 v[70:73], v[204:207], v[196:199], v[70:73]
	v_mfma_f32_16x16x32_bf16 v[66:69], v[220:223], v[196:199], v[66:69]
	s_mov_b32 m0, s67
	s_barrier
	ds_read_b128 v[168:171], v147 offset:49152
	ds_read_b128 v[172:175], v147 offset:50176
	ds_read_b128 v[176:179], v147 offset:51200
	ds_read_b128 v[180:183], v147 offset:52224
	ds_read_b128 v[184:187], v147 offset:53248
	ds_read_b128 v[188:191], v147 offset:54272
	ds_read_b128 v[192:195], v147 offset:55296
	global_load_lds_dwordx4 v0, s[98:99]
	s_mov_b32 m0, s68
	ds_read_b128 v[196:199], v147 offset:56320
	global_load_lds_dwordx4 v136, s[98:99]
	s_barrier
	s_waitcnt lgkmcnt(7)
	v_mfma_f32_16x16x32_bf16 v[62:65], v[152:155], v[168:171], v[62:65]
	v_mfma_f32_16x16x32_bf16 v[58:61], v[160:163], v[168:171], v[58:61]
	s_waitcnt lgkmcnt(5)
	v_mfma_f32_16x16x32_bf16 v[46:49], v[152:155], v[176:179], v[46:49]
	v_mfma_f32_16x16x32_bf16 v[42:45], v[160:163], v[176:179], v[42:45]
	s_waitcnt lgkmcnt(3)
	v_mfma_f32_16x16x32_bf16 v[30:33], v[152:155], v[184:187], v[30:33]
	v_mfma_f32_16x16x32_bf16 v[26:29], v[160:163], v[184:187], v[26:29]
	s_waitcnt lgkmcnt(1)
	v_mfma_f32_16x16x32_bf16 v[14:17], v[152:155], v[192:195], v[14:17]
	v_mfma_f32_16x16x32_bf16 v[10:13], v[160:163], v[192:195], v[10:13]
	v_mfma_f32_16x16x32_bf16 v[62:65], v[156:159], v[172:175], v[62:65]
	v_mfma_f32_16x16x32_bf16 v[58:61], v[164:167], v[172:175], v[58:61]
	v_mfma_f32_16x16x32_bf16 v[46:49], v[156:159], v[180:183], v[46:49]
	v_mfma_f32_16x16x32_bf16 v[42:45], v[164:167], v[180:183], v[42:45]
	v_mfma_f32_16x16x32_bf16 v[30:33], v[156:159], v[188:191], v[30:33]
	v_mfma_f32_16x16x32_bf16 v[26:29], v[164:167], v[188:191], v[26:29]
	s_waitcnt lgkmcnt(0)
	v_mfma_f32_16x16x32_bf16 v[14:17], v[156:159], v[196:199], v[14:17]
	v_mfma_f32_16x16x32_bf16 v[10:13], v[164:167], v[196:199], v[10:13]
	s_barrier
	s_add_i32 s40, s40, s52
	s_mov_b32 m0, s40
	s_add_u32 s30, s30, 0x158080
	s_addc_u32 s31, s31, 0
	global_load_lds_dwordx4 v0, s[30:31]
	s_add_i32 m0, s40, 0x2000
	s_nop 0
	global_load_lds_dwordx4 v136, s[30:31]
	s_waitcnt vmcnt(6)
	s_barrier
	v_mfma_f32_16x16x32_bf16 v[54:57], v[200:203], v[168:171], v[54:57]
	v_mfma_f32_16x16x32_bf16 v[50:53], v[216:219], v[168:171], v[50:53]
	v_mfma_f32_16x16x32_bf16 v[38:41], v[200:203], v[176:179], v[38:41]
	v_mfma_f32_16x16x32_bf16 v[34:37], v[216:219], v[176:179], v[34:37]
	v_mfma_f32_16x16x32_bf16 v[22:25], v[200:203], v[184:187], v[22:25]
	v_mfma_f32_16x16x32_bf16 v[18:21], v[216:219], v[184:187], v[18:21]
	v_mfma_f32_16x16x32_bf16 v[6:9], v[200:203], v[192:195], v[6:9]
	v_mfma_f32_16x16x32_bf16 v[2:5], v[216:219], v[192:195], v[2:5]
	v_mfma_f32_16x16x32_bf16 v[54:57], v[204:207], v[172:175], v[54:57]
	v_mfma_f32_16x16x32_bf16 v[50:53], v[220:223], v[172:175], v[50:53]
	v_mfma_f32_16x16x32_bf16 v[38:41], v[204:207], v[180:183], v[38:41]
	v_mfma_f32_16x16x32_bf16 v[34:37], v[220:223], v[180:183], v[34:37]
	v_mfma_f32_16x16x32_bf16 v[22:25], v[204:207], v[188:191], v[22:25]
	v_mfma_f32_16x16x32_bf16 v[18:21], v[220:223], v[188:191], v[18:21]
	v_mfma_f32_16x16x32_bf16 v[6:9], v[204:207], v[196:199], v[6:9]
	v_mfma_f32_16x16x32_bf16 v[2:5], v[220:223], v[196:199], v[2:5]
	s_add_i32 s78, s78, 2
	s_add_u32 s22, s22, 0x100
	s_addc_u32 s23, s23, 0
	s_cmpk_gt_u32 s78, 0x53
	s_cbranch_scc0 .LBB0_1084
	s_barrier
	s_add_u32 s22, s42, 0xffffff00
	s_addc_u32 s23, s43, -1
	s_and_b64 vcc, exec, s[38:39]
	s_cbranch_vccnz .LBB0_1071
	v_mov_b64_e32 v[2:3], 0
	s_mov_b32 s14, s75
	s_mov_b32 s50, s76
	s_mov_b64 s[6:7], s[12:13]
	s_mov_b32 s69, s77
	v_mov_b64_e32 v[4:5], 0
	v_mov_b64_e32 v[6:7], 0
	v_mov_b64_e32 v[8:9], 0
	v_mov_b64_e32 v[10:11], 0
	v_mov_b64_e32 v[12:13], 0
	v_mov_b64_e32 v[14:15], 0
	v_mov_b64_e32 v[16:17], 0
	v_mov_b64_e32 v[18:19], 0
	v_mov_b64_e32 v[20:21], 0
	v_mov_b64_e32 v[22:23], 0
	v_mov_b64_e32 v[24:25], 0
	v_mov_b64_e32 v[26:27], 0
	v_mov_b64_e32 v[28:29], 0
	v_mov_b64_e32 v[30:31], 0
	v_mov_b64_e32 v[32:33], 0
	v_mov_b64_e32 v[34:35], 0
	v_mov_b64_e32 v[36:37], 0
	v_mov_b64_e32 v[38:39], 0
	v_mov_b64_e32 v[40:41], 0
	v_mov_b64_e32 v[42:43], 0
	v_mov_b64_e32 v[44:45], 0
	v_mov_b64_e32 v[46:47], 0
	v_mov_b64_e32 v[48:49], 0
	v_mov_b64_e32 v[50:51], 0
	v_mov_b64_e32 v[52:53], 0
	v_mov_b64_e32 v[54:55], 0
	v_mov_b64_e32 v[56:57], 0
	v_mov_b64_e32 v[58:59], 0
	v_mov_b64_e32 v[60:61], 0
	v_mov_b64_e32 v[62:63], 0
	v_mov_b64_e32 v[64:65], 0
	v_mov_b64_e32 v[66:67], 0
	v_mov_b64_e32 v[68:69], 0
	v_mov_b64_e32 v[70:71], 0
	v_mov_b64_e32 v[72:73], 0
	v_mov_b64_e32 v[74:75], 0
	v_mov_b64_e32 v[76:77], 0
	v_mov_b64_e32 v[78:79], 0
	v_mov_b64_e32 v[80:81], 0
	v_mov_b64_e32 v[82:83], 0
	v_mov_b64_e32 v[84:85], 0
	v_mov_b64_e32 v[86:87], 0
	v_mov_b64_e32 v[88:89], 0
	v_mov_b64_e32 v[90:91], 0
	v_mov_b64_e32 v[92:93], 0
	v_mov_b64_e32 v[94:95], 0
	v_mov_b64_e32 v[96:97], 0
	v_mov_b64_e32 v[98:99], 0
	v_mov_b64_e32 v[100:101], 0
	v_mov_b64_e32 v[102:103], 0
	v_mov_b64_e32 v[104:105], 0
	v_mov_b64_e32 v[106:107], 0
	v_mov_b64_e32 v[108:109], 0
	v_mov_b64_e32 v[110:111], 0
	v_mov_b64_e32 v[112:113], 0
	v_mov_b64_e32 v[114:115], 0
	v_mov_b64_e32 v[116:117], 0
	v_mov_b64_e32 v[118:119], 0
	v_mov_b64_e32 v[120:121], 0
	v_mov_b64_e32 v[122:123], 0
	v_mov_b64_e32 v[124:125], 0
	v_mov_b64_e32 v[126:127], 0
	v_mov_b64_e32 v[128:129], 0
	s_andn2_b64 vcc, exec, s[0:1]
	s_cbranch_vccnz .LBB0_1072
